# P0 rmsnorm loop + P5 + P9 elementwise phases rewritten by hand (batched row loads, 2 rows per trip, gains in registers, DPP wave sums)
# speedup vs baseline: 1.1617x; 1.0166x over previous
; __device__ __forceinline__ unsigned cvt_pk_bf16(float lo, float hi) { unsigned r; asm volatile("v_cvt_pk_bf16_f32 %0, %1, %2" : "=v"(r) : "v"(lo), "v"(hi)); return r; }
; __global__ void __launch_bounds__(512, 2) mega_fwd(Args a) {
;     ...
;     const float* gain = a.in[9];
;     for (int m = gw; m < MT; m += NGW) {
;       const float* xrow = m < MP ? x_p + (size_t)m * DM : x_s + (size_t)(m - MP) * DM;
;       f32x4 v[8]; float ss = 0.f;
; #pragma unroll
;       for (int j = 0; j < 8; ++j) { v[j] = *(const f32x4*)(xrow + 4 * (64 * j + lane)); ss += (v[j].x * v[j].x + v[j].y * v[j].y) + (v[j].z * v[j].z + v[j].w * v[j].w); }
;       const float r = rsqrtf(wave_sum(ss) * (1.f / DM) + EPS);
; #pragma unroll
;       for (int j = 0; j < 8; ++j) { const f32x4 gn = *(const f32x4*)(gain + 4 * (64 * j + lane)); const f32x4 y = v[j] * r * gn;
;         u32x2 w; w.x = cvt_pk_bf16(y.x, y.y); w.y = cvt_pk_bf16(y.z, y.w); *(u32x2*)(XN + (size_t)m * DM + 4 * (64 * j + lane)) = w; }
.LBB0_18:
	s_or_b64 exec, exec, s[4:5]
	s_cmpk_gt_i32 s96, 0x41ff
	s_cbranch_scc1 .LBB0_24
	s_mov_b64 exec, -1
	v_readlane_b32 s4, v251, 1
	v_readlane_b32 s5, v251, 2
	v_and_b32_e32 v4, 63, v1
	v_lshlrev_b32_e32 v2, 4, v4
	v_add_u32_e32 v3, 0x1000, v2
	v_lshlrev_b32_e32 v4, 3, v4
	v_mov_b32_e32 v177, 0x358637bd
	s_sub_u32 s4, s4, 0xf0
	s_subb_u32 s5, s5, 0
	s_load_dwordx4 s[8:11], s[4:5], 0x0
	s_load_dwordx2 s[14:15], s[4:5], 0x48
	s_load_dwordx2 s[12:13], s[4:5], 0xe0
	s_waitcnt lgkmcnt(0)
	s_add_u32 s12, s12, 0x9900000
	s_addc_u32 s13, s13, 0
	global_load_dwordx4 v[10:13], v2, s[14:15] offset:0
	global_load_dwordx4 v[14:17], v2, s[14:15] offset:1024
	global_load_dwordx4 v[18:21], v2, s[14:15] offset:2048
	global_load_dwordx4 v[22:25], v2, s[14:15] offset:3072
	global_load_dwordx4 v[26:29], v3, s[14:15] offset:0
	global_load_dwordx4 v[30:33], v3, s[14:15] offset:1024
	global_load_dwordx4 v[34:37], v3, s[14:15] offset:2048
	global_load_dwordx4 v[38:41], v3, s[14:15] offset:3072
	s_mov_b32 s16, s96
.Lew0_loop:
	s_cmpk_ge_u32 s16, 0x4200
	s_cbranch_scc1 .Lew0_done
	s_add_u32 s17, s16, s78
	s_cmpk_lt_u32 s16, 0x4000
	s_cselect_b32 s18, s8, s10
	s_cselect_b32 s19, s9, s11
	s_and_b32 s29, s16, 0x3fff
	s_lshl_b32 s29, s29, 13
	s_add_u32 s18, s18, s29
	s_addc_u32 s19, s19, 0
	global_load_dwordx4 v[74:77], v2, s[18:19] offset:0
	global_load_dwordx4 v[78:81], v2, s[18:19] offset:1024
	global_load_dwordx4 v[82:85], v2, s[18:19] offset:2048
	global_load_dwordx4 v[86:89], v2, s[18:19] offset:3072
	global_load_dwordx4 v[90:93], v3, s[18:19] offset:0
	global_load_dwordx4 v[94:97], v3, s[18:19] offset:1024
	global_load_dwordx4 v[98:101], v3, s[18:19] offset:2048
	global_load_dwordx4 v[102:105], v3, s[18:19] offset:3072
	s_cmpk_ge_u32 s17, 0x4200
	s_cbranch_scc1 .Lew0_single
	s_cmpk_lt_u32 s17, 0x4000
	s_cselect_b32 s22, s8, s10
	s_cselect_b32 s23, s9, s11
	s_and_b32 s29, s17, 0x3fff
	s_lshl_b32 s29, s29, 13
	s_add_u32 s22, s22, s29
	s_addc_u32 s23, s23, 0
	global_load_dwordx4 v[106:109], v2, s[22:23] offset:0
	global_load_dwordx4 v[110:113], v2, s[22:23] offset:1024
	global_load_dwordx4 v[114:117], v2, s[22:23] offset:2048
	global_load_dwordx4 v[118:121], v2, s[22:23] offset:3072
	global_load_dwordx4 v[122:125], v3, s[22:23] offset:0
	global_load_dwordx4 v[126:129], v3, s[22:23] offset:1024
	global_load_dwordx4 v[130:133], v3, s[22:23] offset:2048
	global_load_dwordx4 v[134:137], v3, s[22:23] offset:3072
	s_waitcnt vmcnt(8)
	v_mov_b32_e32 v9, 0
	v_mul_f32_e32 v174, v74, v74
	v_fmac_f32_e32 v174, v75, v75
	v_mul_f32_e32 v175, v76, v76
	v_fmac_f32_e32 v175, v77, v77
	v_add_f32_e32 v174, v174, v175
	v_add_f32_e32 v9, v9, v174
	v_mul_f32_e32 v174, v78, v78
	v_fmac_f32_e32 v174, v79, v79
	v_mul_f32_e32 v175, v80, v80
	v_fmac_f32_e32 v175, v81, v81
	v_add_f32_e32 v174, v174, v175
	v_add_f32_e32 v9, v9, v174
	v_mul_f32_e32 v174, v82, v82
	v_fmac_f32_e32 v174, v83, v83
	v_mul_f32_e32 v175, v84, v84
	v_fmac_f32_e32 v175, v85, v85
	v_add_f32_e32 v174, v174, v175
	v_add_f32_e32 v9, v9, v174
	v_mul_f32_e32 v174, v86, v86
	v_fmac_f32_e32 v174, v87, v87
	v_mul_f32_e32 v175, v88, v88
	v_fmac_f32_e32 v175, v89, v89
	v_add_f32_e32 v174, v174, v175
	v_add_f32_e32 v9, v9, v174
	v_mul_f32_e32 v174, v90, v90
	v_fmac_f32_e32 v174, v91, v91
	v_mul_f32_e32 v175, v92, v92
	v_fmac_f32_e32 v175, v93, v93
	v_add_f32_e32 v174, v174, v175
	v_add_f32_e32 v9, v9, v174
	v_mul_f32_e32 v174, v94, v94
	v_fmac_f32_e32 v174, v95, v95
	v_mul_f32_e32 v175, v96, v96
	v_fmac_f32_e32 v175, v97, v97
	v_add_f32_e32 v174, v174, v175
	v_add_f32_e32 v9, v9, v174
	v_mul_f32_e32 v174, v98, v98
	v_fmac_f32_e32 v174, v99, v99
	v_mul_f32_e32 v175, v100, v100
	v_fmac_f32_e32 v175, v101, v101
	v_add_f32_e32 v174, v174, v175
	v_add_f32_e32 v9, v9, v174
	v_mul_f32_e32 v174, v102, v102
	v_fmac_f32_e32 v174, v103, v103
	v_mul_f32_e32 v175, v104, v104
	v_fmac_f32_e32 v175, v105, v105
	v_add_f32_e32 v174, v174, v175
	v_add_f32_e32 v9, v9, v174
	s_nop 1
	v_add_f32_dpp v9, v9, v9 quad_perm:[1,0,3,2] row_mask:0xf bank_mask:0xf
	s_nop 1
	v_add_f32_dpp v9, v9, v9 quad_perm:[2,3,0,1] row_mask:0xf bank_mask:0xf
	s_nop 1
	v_add_f32_dpp v9, v9, v9 row_half_mirror row_mask:0xf bank_mask:0xf
	s_nop 1
	v_add_f32_dpp v9, v9, v9 row_mirror row_mask:0xf bank_mask:0xf
	s_nop 1
	v_add_f32_dpp v9, v9, v9 row_bcast:15 row_mask:0xa bank_mask:0xf
	s_nop 1
	v_add_f32_dpp v9, v9, v9 row_bcast:31 row_mask:0xc bank_mask:0xf
	s_nop 1
	v_readlane_b32 s28, v9, 63
	s_nop 1
	v_mov_b32_e32 v174, s28
	v_fmamk_f32 v174, v174, 0x3a000000, v177
	v_rsq_f32_e32 v176, v174
	s_nop 0
	v_mul_f32_e32 v5, v74, v176
	v_mul_f32_e32 v6, v75, v176
	v_mul_f32_e32 v7, v76, v176
	v_mul_f32_e32 v8, v77, v176
	v_mul_f32_e32 v5, v5, v10
	v_mul_f32_e32 v6, v6, v11
	v_mul_f32_e32 v7, v7, v12
	v_mul_f32_e32 v8, v8, v13
	v_cvt_pk_bf16_f32 v138, v5, v6
	v_cvt_pk_bf16_f32 v139, v7, v8
	v_mul_f32_e32 v5, v78, v176
	v_mul_f32_e32 v6, v79, v176
	v_mul_f32_e32 v7, v80, v176
	v_mul_f32_e32 v8, v81, v176
	v_mul_f32_e32 v5, v5, v14
	v_mul_f32_e32 v6, v6, v15
	v_mul_f32_e32 v7, v7, v16
	v_mul_f32_e32 v8, v8, v17
	v_cvt_pk_bf16_f32 v140, v5, v6
	v_cvt_pk_bf16_f32 v141, v7, v8
	v_mul_f32_e32 v5, v82, v176
	v_mul_f32_e32 v6, v83, v176
	v_mul_f32_e32 v7, v84, v176
	v_mul_f32_e32 v8, v85, v176
	v_mul_f32_e32 v5, v5, v18
	v_mul_f32_e32 v6, v6, v19
	v_mul_f32_e32 v7, v7, v20
	v_mul_f32_e32 v8, v8, v21
	v_cvt_pk_bf16_f32 v142, v5, v6
	v_cvt_pk_bf16_f32 v143, v7, v8
	v_mul_f32_e32 v5, v86, v176
	v_mul_f32_e32 v6, v87, v176
	v_mul_f32_e32 v7, v88, v176
	v_mul_f32_e32 v8, v89, v176
	v_mul_f32_e32 v5, v5, v22
	v_mul_f32_e32 v6, v6, v23
	v_mul_f32_e32 v7, v7, v24
	v_mul_f32_e32 v8, v8, v25
; __device__ __forceinline__ unsigned cvt_pk_bf16(float lo, float hi) { unsigned r; asm volatile("v_cvt_pk_bf16_f32 %0, %1, %2" : "=v"(r) : "v"(lo), "v"(hi)); return r; }
; __global__ void __launch_bounds__(512, 2) mega_fwd(Args a) {
;     ...
;       const float r = rsqrtf(wave_sum(ss) * (1.f / DM) + EPS);
; #pragma unroll
;       for (int j = 0; j < 8; ++j) { const f32x4 gn = *(const f32x4*)(gain + 4 * (64 * j + lane)); const f32x4 y = v[j] * r * gn;
;         u32x2 w; w.x = cvt_pk_bf16(y.x, y.y); w.y = cvt_pk_bf16(y.z, y.w); *(u32x2*)(XN + (size_t)m * DM + 4 * (64 * j + lane)) = w; }
	v_cvt_pk_bf16_f32 v144, v5, v6
	v_cvt_pk_bf16_f32 v145, v7, v8
	v_mul_f32_e32 v5, v90, v176
	v_mul_f32_e32 v6, v91, v176
	v_mul_f32_e32 v7, v92, v176
	v_mul_f32_e32 v8, v93, v176
	v_mul_f32_e32 v5, v5, v26
	v_mul_f32_e32 v6, v6, v27
	v_mul_f32_e32 v7, v7, v28
	v_mul_f32_e32 v8, v8, v29
	v_cvt_pk_bf16_f32 v146, v5, v6
	v_cvt_pk_bf16_f32 v147, v7, v8
	v_mul_f32_e32 v5, v94, v176
	v_mul_f32_e32 v6, v95, v176
	v_mul_f32_e32 v7, v96, v176
	v_mul_f32_e32 v8, v97, v176
	v_mul_f32_e32 v5, v5, v30
	v_mul_f32_e32 v6, v6, v31
	v_mul_f32_e32 v7, v7, v32
	v_mul_f32_e32 v8, v8, v33
	v_cvt_pk_bf16_f32 v148, v5, v6
	v_cvt_pk_bf16_f32 v149, v7, v8
	v_mul_f32_e32 v5, v98, v176
	v_mul_f32_e32 v6, v99, v176
	v_mul_f32_e32 v7, v100, v176
	v_mul_f32_e32 v8, v101, v176
	v_mul_f32_e32 v5, v5, v34
	v_mul_f32_e32 v6, v6, v35
	v_mul_f32_e32 v7, v7, v36
	v_mul_f32_e32 v8, v8, v37
	v_cvt_pk_bf16_f32 v150, v5, v6
	v_cvt_pk_bf16_f32 v151, v7, v8
	v_mul_f32_e32 v5, v102, v176
	v_mul_f32_e32 v6, v103, v176
	v_mul_f32_e32 v7, v104, v176
	v_mul_f32_e32 v8, v105, v176
	v_mul_f32_e32 v5, v5, v38
	v_mul_f32_e32 v6, v6, v39
	v_mul_f32_e32 v7, v7, v40
	v_mul_f32_e32 v8, v8, v41
	v_cvt_pk_bf16_f32 v152, v5, v6
	v_cvt_pk_bf16_f32 v153, v7, v8
	s_lshl_b32 s29, s16, 12
	s_add_u32 s20, s12, s29
	s_addc_u32 s21, s13, 0
	global_store_dwordx2 v4, v[138:139], s[20:21] offset:0
	global_store_dwordx2 v4, v[140:141], s[20:21] offset:512
	global_store_dwordx2 v4, v[142:143], s[20:21] offset:1024
	global_store_dwordx2 v4, v[144:145], s[20:21] offset:1536
	global_store_dwordx2 v4, v[146:147], s[20:21] offset:2048
	global_store_dwordx2 v4, v[148:149], s[20:21] offset:2560
	global_store_dwordx2 v4, v[150:151], s[20:21] offset:3072
	global_store_dwordx2 v4, v[152:153], s[20:21] offset:3584
	s_waitcnt vmcnt(8)
	v_mov_b32_e32 v9, 0
	v_mul_f32_e32 v174, v106, v106
	v_fmac_f32_e32 v174, v107, v107
	v_mul_f32_e32 v175, v108, v108
	v_fmac_f32_e32 v175, v109, v109
	v_add_f32_e32 v174, v174, v175
	v_add_f32_e32 v9, v9, v174
	v_mul_f32_e32 v174, v110, v110
	v_fmac_f32_e32 v174, v111, v111
	v_mul_f32_e32 v175, v112, v112
	v_fmac_f32_e32 v175, v113, v113
	v_add_f32_e32 v174, v174, v175
	v_add_f32_e32 v9, v9, v174
	v_mul_f32_e32 v174, v114, v114
	v_fmac_f32_e32 v174, v115, v115
	v_mul_f32_e32 v175, v116, v116
	v_fmac_f32_e32 v175, v117, v117
	v_add_f32_e32 v174, v174, v175
	v_add_f32_e32 v9, v9, v174
	v_mul_f32_e32 v174, v118, v118
	v_fmac_f32_e32 v174, v119, v119
	v_mul_f32_e32 v175, v120, v120
	v_fmac_f32_e32 v175, v121, v121
	v_add_f32_e32 v174, v174, v175
	v_add_f32_e32 v9, v9, v174
	v_mul_f32_e32 v174, v122, v122
	v_fmac_f32_e32 v174, v123, v123
	v_mul_f32_e32 v175, v124, v124
	v_fmac_f32_e32 v175, v125, v125
	v_add_f32_e32 v174, v174, v175
	v_add_f32_e32 v9, v9, v174
	v_mul_f32_e32 v174, v126, v126
	v_fmac_f32_e32 v174, v127, v127
	v_mul_f32_e32 v175, v128, v128
	v_fmac_f32_e32 v175, v129, v129
	v_add_f32_e32 v174, v174, v175
	v_add_f32_e32 v9, v9, v174
	v_mul_f32_e32 v174, v130, v130
	v_fmac_f32_e32 v174, v131, v131
	v_mul_f32_e32 v175, v132, v132
	v_fmac_f32_e32 v175, v133, v133
	v_add_f32_e32 v174, v174, v175
	v_add_f32_e32 v9, v9, v174
	v_mul_f32_e32 v174, v134, v134
	v_fmac_f32_e32 v174, v135, v135
	v_mul_f32_e32 v175, v136, v136
	v_fmac_f32_e32 v175, v137, v137
	v_add_f32_e32 v174, v174, v175
	v_add_f32_e32 v9, v9, v174
	s_nop 1
	v_add_f32_dpp v9, v9, v9 quad_perm:[1,0,3,2] row_mask:0xf bank_mask:0xf
	s_nop 1
	v_add_f32_dpp v9, v9, v9 quad_perm:[2,3,0,1] row_mask:0xf bank_mask:0xf
	s_nop 1
	v_add_f32_dpp v9, v9, v9 row_half_mirror row_mask:0xf bank_mask:0xf
	s_nop 1
	v_add_f32_dpp v9, v9, v9 row_mirror row_mask:0xf bank_mask:0xf
	s_nop 1
	v_add_f32_dpp v9, v9, v9 row_bcast:15 row_mask:0xa bank_mask:0xf
	s_nop 1
	v_add_f32_dpp v9, v9, v9 row_bcast:31 row_mask:0xc bank_mask:0xf
	s_nop 1
	v_readlane_b32 s28, v9, 63
	s_nop 1
	v_mov_b32_e32 v174, s28
	v_fmamk_f32 v174, v174, 0x3a000000, v177
	v_rsq_f32_e32 v176, v174
	s_nop 0
	v_mul_f32_e32 v5, v106, v176
	v_mul_f32_e32 v6, v107, v176
	v_mul_f32_e32 v7, v108, v176
	v_mul_f32_e32 v8, v109, v176
	v_mul_f32_e32 v5, v5, v10
	v_mul_f32_e32 v6, v6, v11
	v_mul_f32_e32 v7, v7, v12
	v_mul_f32_e32 v8, v8, v13
	v_cvt_pk_bf16_f32 v154, v5, v6
	v_cvt_pk_bf16_f32 v155, v7, v8
	v_mul_f32_e32 v5, v110, v176
	v_mul_f32_e32 v6, v111, v176
	v_mul_f32_e32 v7, v112, v176
	v_mul_f32_e32 v8, v113, v176
	v_mul_f32_e32 v5, v5, v14
	v_mul_f32_e32 v6, v6, v15
	v_mul_f32_e32 v7, v7, v16
	v_mul_f32_e32 v8, v8, v17
	v_cvt_pk_bf16_f32 v156, v5, v6
	v_cvt_pk_bf16_f32 v157, v7, v8
	v_mul_f32_e32 v5, v114, v176
	v_mul_f32_e32 v6, v115, v176
	v_mul_f32_e32 v7, v116, v176
	v_mul_f32_e32 v8, v117, v176
	v_mul_f32_e32 v5, v5, v18
	v_mul_f32_e32 v6, v6, v19
	v_mul_f32_e32 v7, v7, v20
	v_mul_f32_e32 v8, v8, v21
	v_cvt_pk_bf16_f32 v158, v5, v6
	v_cvt_pk_bf16_f32 v159, v7, v8
	v_mul_f32_e32 v5, v118, v176
	v_mul_f32_e32 v6, v119, v176
	v_mul_f32_e32 v7, v120, v176
	v_mul_f32_e32 v8, v121, v176
	v_mul_f32_e32 v5, v5, v22
	v_mul_f32_e32 v6, v6, v23
	v_mul_f32_e32 v7, v7, v24
	v_mul_f32_e32 v8, v8, v25
	v_cvt_pk_bf16_f32 v160, v5, v6
	v_cvt_pk_bf16_f32 v161, v7, v8
	v_mul_f32_e32 v5, v122, v176
	v_mul_f32_e32 v6, v123, v176
	v_mul_f32_e32 v7, v124, v176
	v_mul_f32_e32 v8, v125, v176
	v_mul_f32_e32 v5, v5, v26
	v_mul_f32_e32 v6, v6, v27
	v_mul_f32_e32 v7, v7, v28
	v_mul_f32_e32 v8, v8, v29
	v_cvt_pk_bf16_f32 v162, v5, v6
	v_cvt_pk_bf16_f32 v163, v7, v8
	v_mul_f32_e32 v5, v126, v176
	v_mul_f32_e32 v6, v127, v176
	v_mul_f32_e32 v7, v128, v176
	v_mul_f32_e32 v8, v129, v176
	v_mul_f32_e32 v5, v5, v30
	v_mul_f32_e32 v6, v6, v31
	v_mul_f32_e32 v7, v7, v32
	v_mul_f32_e32 v8, v8, v33
	v_cvt_pk_bf16_f32 v166, v5, v6
	v_cvt_pk_bf16_f32 v167, v7, v8
	v_mul_f32_e32 v5, v130, v176
	v_mul_f32_e32 v6, v131, v176
	v_mul_f32_e32 v7, v132, v176
	v_mul_f32_e32 v8, v133, v176
	v_mul_f32_e32 v5, v5, v34
	v_mul_f32_e32 v6, v6, v35
	v_mul_f32_e32 v7, v7, v36
	v_mul_f32_e32 v8, v8, v37
	v_cvt_pk_bf16_f32 v168, v5, v6
	v_cvt_pk_bf16_f32 v169, v7, v8
	v_mul_f32_e32 v5, v134, v176
	v_mul_f32_e32 v6, v135, v176
	v_mul_f32_e32 v7, v136, v176
	v_mul_f32_e32 v8, v137, v176
	v_mul_f32_e32 v5, v5, v38
	v_mul_f32_e32 v6, v6, v39
	v_mul_f32_e32 v7, v7, v40
	v_mul_f32_e32 v8, v8, v41
	v_cvt_pk_bf16_f32 v172, v5, v6
	v_cvt_pk_bf16_f32 v173, v7, v8
	s_lshl_b32 s29, s17, 12
	s_add_u32 s26, s12, s29
	s_addc_u32 s27, s13, 0
	global_store_dwordx2 v4, v[154:155], s[26:27] offset:0
	global_store_dwordx2 v4, v[156:157], s[26:27] offset:512
	global_store_dwordx2 v4, v[158:159], s[26:27] offset:1024
	global_store_dwordx2 v4, v[160:161], s[26:27] offset:1536
	global_store_dwordx2 v4, v[162:163], s[26:27] offset:2048
	global_store_dwordx2 v4, v[166:167], s[26:27] offset:2560
	global_store_dwordx2 v4, v[168:169], s[26:27] offset:3072
	global_store_dwordx2 v4, v[172:173], s[26:27] offset:3584
	s_add_u32 s16, s17, s78
	s_branch .Lew0_loop
; __device__ __forceinline__ unsigned cvt_pk_bf16(float lo, float hi) { unsigned r; asm volatile("v_cvt_pk_bf16_f32 %0, %1, %2" : "=v"(r) : "v"(lo), "v"(hi)); return r; }
; __global__ void __launch_bounds__(512, 2) mega_fwd(Args a) {
;     ...
;       const float* xrow = m < MP ? x_p + (size_t)m * DM : x_s + (size_t)(m - MP) * DM;
;       f32x4 v[8]; float ss = 0.f;
; #pragma unroll
;       for (int j = 0; j < 8; ++j) { v[j] = *(const f32x4*)(xrow + 4 * (64 * j + lane)); ss += (v[j].x * v[j].x + v[j].y * v[j].y) + (v[j].z * v[j].z + v[j].w * v[j].w); }
;       const float r = rsqrtf(wave_sum(ss) * (1.f / DM) + EPS);
; #pragma unroll
;       for (int j = 0; j < 8; ++j) { const f32x4 gn = *(const f32x4*)(gain + 4 * (64 * j + lane)); const f32x4 y = v[j] * r * gn;
;         u32x2 w; w.x = cvt_pk_bf16(y.x, y.y); w.y = cvt_pk_bf16(y.z, y.w); *(u32x2*)(XN + (size_t)m * DM + 4 * (64 * j + lane)) = w; }
.Lew0_single:
	s_waitcnt vmcnt(0)
	v_mov_b32_e32 v9, 0
	v_mul_f32_e32 v174, v74, v74
	v_fmac_f32_e32 v174, v75, v75
	v_mul_f32_e32 v175, v76, v76
	v_fmac_f32_e32 v175, v77, v77
	v_add_f32_e32 v174, v174, v175
	v_add_f32_e32 v9, v9, v174
	v_mul_f32_e32 v174, v78, v78
	v_fmac_f32_e32 v174, v79, v79
	v_mul_f32_e32 v175, v80, v80
	v_fmac_f32_e32 v175, v81, v81
	v_add_f32_e32 v174, v174, v175
	v_add_f32_e32 v9, v9, v174
	v_mul_f32_e32 v174, v82, v82
	v_fmac_f32_e32 v174, v83, v83
	v_mul_f32_e32 v175, v84, v84
	v_fmac_f32_e32 v175, v85, v85
	v_add_f32_e32 v174, v174, v175
	v_add_f32_e32 v9, v9, v174
	v_mul_f32_e32 v174, v86, v86
	v_fmac_f32_e32 v174, v87, v87
	v_mul_f32_e32 v175, v88, v88
	v_fmac_f32_e32 v175, v89, v89
	v_add_f32_e32 v174, v174, v175
	v_add_f32_e32 v9, v9, v174
	v_mul_f32_e32 v174, v90, v90
	v_fmac_f32_e32 v174, v91, v91
	v_mul_f32_e32 v175, v92, v92
	v_fmac_f32_e32 v175, v93, v93
	v_add_f32_e32 v174, v174, v175
	v_add_f32_e32 v9, v9, v174
	v_mul_f32_e32 v174, v94, v94
	v_fmac_f32_e32 v174, v95, v95
	v_mul_f32_e32 v175, v96, v96
	v_fmac_f32_e32 v175, v97, v97
	v_add_f32_e32 v174, v174, v175
	v_add_f32_e32 v9, v9, v174
	v_mul_f32_e32 v174, v98, v98
	v_fmac_f32_e32 v174, v99, v99
	v_mul_f32_e32 v175, v100, v100
	v_fmac_f32_e32 v175, v101, v101
	v_add_f32_e32 v174, v174, v175
	v_add_f32_e32 v9, v9, v174
	v_mul_f32_e32 v174, v102, v102
	v_fmac_f32_e32 v174, v103, v103
	v_mul_f32_e32 v175, v104, v104
	v_fmac_f32_e32 v175, v105, v105
	v_add_f32_e32 v174, v174, v175
	v_add_f32_e32 v9, v9, v174
	s_nop 1
	v_add_f32_dpp v9, v9, v9 quad_perm:[1,0,3,2] row_mask:0xf bank_mask:0xf
	s_nop 1
	v_add_f32_dpp v9, v9, v9 quad_perm:[2,3,0,1] row_mask:0xf bank_mask:0xf
	s_nop 1
	v_add_f32_dpp v9, v9, v9 row_half_mirror row_mask:0xf bank_mask:0xf
	s_nop 1
	v_add_f32_dpp v9, v9, v9 row_mirror row_mask:0xf bank_mask:0xf
	s_nop 1
	v_add_f32_dpp v9, v9, v9 row_bcast:15 row_mask:0xa bank_mask:0xf
	s_nop 1
	v_add_f32_dpp v9, v9, v9 row_bcast:31 row_mask:0xc bank_mask:0xf
	s_nop 1
	v_readlane_b32 s28, v9, 63
	s_nop 1
	v_mov_b32_e32 v174, s28
	v_fmamk_f32 v174, v174, 0x3a000000, v177
	v_rsq_f32_e32 v176, v174
	s_nop 0
	v_mul_f32_e32 v5, v74, v176
	v_mul_f32_e32 v6, v75, v176
	v_mul_f32_e32 v7, v76, v176
	v_mul_f32_e32 v8, v77, v176
	v_mul_f32_e32 v5, v5, v10
	v_mul_f32_e32 v6, v6, v11
	v_mul_f32_e32 v7, v7, v12
	v_mul_f32_e32 v8, v8, v13
	v_cvt_pk_bf16_f32 v138, v5, v6
	v_cvt_pk_bf16_f32 v139, v7, v8
	v_mul_f32_e32 v5, v78, v176
	v_mul_f32_e32 v6, v79, v176
	v_mul_f32_e32 v7, v80, v176
	v_mul_f32_e32 v8, v81, v176
	v_mul_f32_e32 v5, v5, v14
	v_mul_f32_e32 v6, v6, v15
	v_mul_f32_e32 v7, v7, v16
	v_mul_f32_e32 v8, v8, v17
	v_cvt_pk_bf16_f32 v140, v5, v6
	v_cvt_pk_bf16_f32 v141, v7, v8
	v_mul_f32_e32 v5, v82, v176
	v_mul_f32_e32 v6, v83, v176
	v_mul_f32_e32 v7, v84, v176
	v_mul_f32_e32 v8, v85, v176
	v_mul_f32_e32 v5, v5, v18
	v_mul_f32_e32 v6, v6, v19
	v_mul_f32_e32 v7, v7, v20
	v_mul_f32_e32 v8, v8, v21
	v_cvt_pk_bf16_f32 v142, v5, v6
	v_cvt_pk_bf16_f32 v143, v7, v8
	v_mul_f32_e32 v5, v86, v176
	v_mul_f32_e32 v6, v87, v176
	v_mul_f32_e32 v7, v88, v176
	v_mul_f32_e32 v8, v89, v176
	v_mul_f32_e32 v5, v5, v22
	v_mul_f32_e32 v6, v6, v23
	v_mul_f32_e32 v7, v7, v24
	v_mul_f32_e32 v8, v8, v25
	v_cvt_pk_bf16_f32 v144, v5, v6
	v_cvt_pk_bf16_f32 v145, v7, v8
	v_mul_f32_e32 v5, v90, v176
	v_mul_f32_e32 v6, v91, v176
	v_mul_f32_e32 v7, v92, v176
	v_mul_f32_e32 v8, v93, v176
	v_mul_f32_e32 v5, v5, v26
	v_mul_f32_e32 v6, v6, v27
	v_mul_f32_e32 v7, v7, v28
	v_mul_f32_e32 v8, v8, v29
	v_cvt_pk_bf16_f32 v146, v5, v6
	v_cvt_pk_bf16_f32 v147, v7, v8
	v_mul_f32_e32 v5, v94, v176
	v_mul_f32_e32 v6, v95, v176
	v_mul_f32_e32 v7, v96, v176
	v_mul_f32_e32 v8, v97, v176
	v_mul_f32_e32 v5, v5, v30
	v_mul_f32_e32 v6, v6, v31
	v_mul_f32_e32 v7, v7, v32
	v_mul_f32_e32 v8, v8, v33
	v_cvt_pk_bf16_f32 v148, v5, v6
	v_cvt_pk_bf16_f32 v149, v7, v8
	v_mul_f32_e32 v5, v98, v176
	v_mul_f32_e32 v6, v99, v176
	v_mul_f32_e32 v7, v100, v176
	v_mul_f32_e32 v8, v101, v176
	v_mul_f32_e32 v5, v5, v34
	v_mul_f32_e32 v6, v6, v35
	v_mul_f32_e32 v7, v7, v36
	v_mul_f32_e32 v8, v8, v37
	v_cvt_pk_bf16_f32 v150, v5, v6
	v_cvt_pk_bf16_f32 v151, v7, v8
	v_mul_f32_e32 v5, v102, v176
	v_mul_f32_e32 v6, v103, v176
	v_mul_f32_e32 v7, v104, v176
	v_mul_f32_e32 v8, v105, v176
	v_mul_f32_e32 v5, v5, v38
	v_mul_f32_e32 v6, v6, v39
	v_mul_f32_e32 v7, v7, v40
	v_mul_f32_e32 v8, v8, v41
	v_cvt_pk_bf16_f32 v152, v5, v6
	v_cvt_pk_bf16_f32 v153, v7, v8
	s_lshl_b32 s29, s16, 12
	s_add_u32 s20, s12, s29
	s_addc_u32 s21, s13, 0
	global_store_dwordx2 v4, v[138:139], s[20:21] offset:0
	global_store_dwordx2 v4, v[140:141], s[20:21] offset:512
	global_store_dwordx2 v4, v[142:143], s[20:21] offset:1024
	global_store_dwordx2 v4, v[144:145], s[20:21] offset:1536
	global_store_dwordx2 v4, v[146:147], s[20:21] offset:2048
	global_store_dwordx2 v4, v[148:149], s[20:21] offset:2560
	global_store_dwordx2 v4, v[150:151], s[20:21] offset:3072
	global_store_dwordx2 v4, v[152:153], s[20:21] offset:3584
; __device__ __forceinline__ unsigned xb_ld(unsigned* p)              { return __hip_atomic_load(p, __ATOMIC_RELAXED, __HIP_MEMORY_SCOPE_AGENT); }
; __device__ __forceinline__ unsigned xb_add(unsigned* p, unsigned v) { return __hip_atomic_fetch_add(p, v, __ATOMIC_RELAXED, __HIP_MEMORY_SCOPE_AGENT); }
; #define XB_SPIN(cond, bar) do { unsigned _sp = 0; while (cond) { __builtin_amdgcn_s_sleep(1); \
;     if ((++_sp & 255u) == 0u) { if (xb_ld(&(bar)[XB_TMO])) break; if (_sp > XB_SPIN_CAP) { atomicAdd(&(bar)[XB_TMO], 1u); break; } } } } while (0)
; __device__ __forceinline__ void xcd_barrier(const XcdBarrier& b) {
;     asm volatile("s_waitcnt vmcnt(0)" ::: "memory");
;     __syncthreads();
;     if (threadIdx.x == 0) {
;         unsigned* bar = b.bar;
;         __builtin_amdgcn_s_waitcnt(0);
;         unsigned nloc = b.st[0], nx = b.st[1];
;         if (nloc == 0u) { xcd_barrier_complete(bar, b.x, nloc, nx); b.st[0] = nloc; b.st[1] = nx; }
;         const unsigned old = xb_add(&bar[XB_XSUB(b.x)], 1u);
;         const unsigned gen = old / nloc;
;         if (old + 1u == (gen + 1u) * nloc) {
;             __builtin_amdgcn_fence(__ATOMIC_RELEASE, "agent");
;             asm volatile("s_waitcnt vmcnt(0)" ::: "memory");
;             const unsigned og = xb_add(&bar[XB_TOP], 1u);
;             const unsigned tg = og / nx;
;             if (og + 1u == (tg + 1u) * nx) xb_add(&bar[XB_TOPGEN], 1u);
;             else XB_SPIN(xb_ld(&bar[XB_TOPGEN]) == tg, bar);
;             __builtin_amdgcn_fence(__ATOMIC_ACQUIRE, "agent");
;             xb_add(&bar[XB_XGEN(b.x)], 1u);
;             asm volatile("s_waitcnt vmcnt(0)" ::: "memory");
;         } else {
;             XB_SPIN(xb_ld(&bar[XB_XGEN(b.x)]) == gen, bar);
;             __builtin_amdgcn_fence(__ATOMIC_ACQUIRE, "agent");
;             asm volatile("s_waitcnt vmcnt(0)" ::: "memory");
;         }
;     }
;     __syncthreads();
; }
.Lew0_done:
.LBB0_24:
	s_load_dwordx16 s[4:19], s[0:1], 0x80
	s_cmp_gt_i32 s87, 1
	s_cselect_b64 s[0:1], -1, 0
	s_and_b64 s[2:3], s[2:3], s[0:1]
	s_andn2_b64 vcc, exec, s[2:3]
	s_waitcnt lgkmcnt(0)
	v_writelane_b32 v251, s4, 32
	s_nop 1
	v_writelane_b32 v251, s5, 33
	v_writelane_b32 v251, s6, 34
	v_writelane_b32 v251, s7, 35
	v_writelane_b32 v251, s8, 36
	v_writelane_b32 v251, s9, 37
	v_writelane_b32 v251, s10, 38
	v_writelane_b32 v251, s11, 39
	v_writelane_b32 v251, s12, 40
	v_writelane_b32 v251, s13, 41
	v_writelane_b32 v251, s14, 42
	v_writelane_b32 v251, s15, 43
	v_writelane_b32 v251, s16, 44
	v_writelane_b32 v251, s17, 45
	v_writelane_b32 v251, s18, 46
	v_writelane_b32 v251, s19, 47
	s_cbranch_vccnz .LBB0_92
	s_cmp_gt_i32 s86, -1
	s_mov_b64 s[2:3], -1
	s_cbranch_scc0 .LBB0_79
	s_waitcnt vmcnt(0)
	s_barrier
	s_mov_b64 s[2:3], exec
	v_readlane_b32 s4, v251, 19
	v_readlane_b32 s5, v251, 20
	s_and_b64 s[4:5], s[2:3], s[4:5]
	s_mov_b64 exec, s[4:5]
	s_cbranch_execz .LBB0_78
	s_add_i32 s4, 0, 0x25fa0
	v_mov_b32_e32 v2, s4
	s_waitcnt vmcnt(0) expcnt(0) lgkmcnt(0)
	ds_read_b32 v4, v2
	s_add_i32 s4, 0, 0x25fa4
	v_mov_b32_e32 v2, s4
	ds_read_b32 v2, v2
	s_waitcnt lgkmcnt(1)
	v_cmp_ne_u32_e32 vcc, 0, v4
	s_cbranch_vccnz .LBB0_42
	v_readlane_b32 s4, v251, 0
	s_mul_i32 s24, s83, s4
	s_add_u32 s4, s84, 0x225c8200
	s_addc_u32 s5, s85, 0
	s_add_u32 s6, s84, 0x225c8400
	s_addc_u32 s7, s85, 0
	s_add_u32 s8, s84, 0x225c8500
	s_addc_u32 s9, s85, 0
	s_add_u32 s10, s84, 0x225c8600
	s_addc_u32 s11, s85, 0
	s_add_u32 s12, s84, 0x225c8700
	s_addc_u32 s13, s85, 0
	s_add_u32 s14, s84, 0x225c8800
	s_addc_u32 s15, s85, 0
	s_add_u32 s16, s84, 0x225c8900
	s_addc_u32 s17, s85, 0
	s_add_u32 s18, s84, 0x225c8a00
	s_addc_u32 s19, s85, 0
	s_add_u32 s20, s84, 0x225c8b00
	s_addc_u32 s21, s85, 0
	s_add_u32 s22, s84, 0x225c8c00
	s_addc_u32 s23, s85, 0
	s_add_u32 s28, s84, 0x225c8d00
	s_addc_u32 s29, s85, 0
	s_add_u32 s30, s84, 0x225c8e00
	s_addc_u32 s31, s85, 0
	s_add_u32 s34, s84, 0x225c8f00
	s_addc_u32 s35, s85, 0
	s_add_u32 s36, s84, 0x225c9000
	s_addc_u32 s37, s85, 0
	s_add_u32 s38, s84, 0x225c9100
	s_addc_u32 s39, s85, 0
	s_add_u32 s42, s84, 0x225c9200
	s_addc_u32 s43, s85, 0
	s_add_u32 s44, s84, 0x225c9300
	s_mul_i32 s24, s24, s82
	s_addc_u32 s45, s85, 0
	s_mov_b32 s25, 1
	v_mov_b32_e32 v18, 0
	s_branch .LBB0_30

; __device__ __forceinline__ float bflo(unsigned w) { return __uint_as_float(w << 16); }
; __device__ __forceinline__ float bfhi(unsigned w) { return __uint_as_float(w & 0xffff0000u); }
; __global__ void __launch_bounds__(512, 2) mega_fwd(Args a) {
;     ...
;   if (IN(9)) {
;     const float* g2 = a.in[26];
;     for (int m = gw; m < MT; m += NGW) {
;       f32x4 hin[8];
; #pragma unroll
;       for (int j = 0; j < 8; ++j) hin[j] = *(const f32x4*)(out + O_Y + (size_t)m * DM + 4 * (64 * j + lane));
;       f32x4 v[8]; float ss = 0.f;
; #pragma unroll
;       for (int j = 0; j < 8; ++j) {
;         if (m < MP) { const u32x2 w = *(const u32x2*)(MO + (size_t)m * DM + 4 * (64 * j + lane)); v[j] = (f32x4){bflo(w.x), bfhi(w.x), bflo(w.y), bfhi(w.y)}; }
;         else { v[j] = (f32x4){0.f, 0.f, 0.f, 0.f};
; #pragma unroll
;           for (int ks = 0; ks < 16; ++ks) v[j] += *(const f32x4*)(PART + ((size_t)ks * MSAMP + (m - MP)) * DM + 4 * (64 * j + lane)); }
.LBB0_1556:
	s_cmp_lt_i32 s86, 10
	s_cselect_b64 s[0:1], -1, 0
	s_and_b64 s[0:1], s[0:1], s[2:3]
	s_and_b64 s[0:1], s[0:1], s[64:65]
	s_andn2_b64 vcc, exec, s[0:1]
	s_cbranch_vccnz .LBB0_1591
	s_mov_b64 exec, -1
	v_readlane_b32 s2, v251, 1
	v_readlane_b32 s3, v251, 2
	v_and_b32_e32 v4, 63, v1
	v_lshlrev_b32_e32 v2, 4, v4
	v_add_u32_e32 v3, 0x1000, v2
	v_lshlrev_b32_e32 v4, 3, v4
	v_mov_b32_e32 v177, 0x358637bd
	s_sub_u32 s2, s2, 0xf0
	s_subb_u32 s3, s3, 0
	s_load_dwordx2 s[20:21], s[2:3], 0xd0
	s_load_dwordx2 s[8:9], s[2:3], 0xd8
	s_load_dwordx2 s[12:13], s[2:3], 0xe0
	s_waitcnt lgkmcnt(0)
	s_add_u32 s16, s12, 0x22600000
	s_addc_u32 s17, s13, 0
	s_add_u32 s12, s12, 0x2ec00000
	s_addc_u32 s13, s13, 0
	s_and_b32 s97, s96, 3
	s_cmp_lg_u32 s97, 0
	s_cbranch_scc1 .Lew9_prompt
	s_lshr_b32 s18, s96, 2
.Lew9_samp_loop:
	s_cmpk_ge_u32 s18, 0x200
	s_cbranch_scc1 .Lew9_prompt
	s_lshl_b32 s97, s18, 13
	s_add_u32 s24, s16, s97
	s_addc_u32 s25, s17, 0
	global_load_dwordx4 v[106:109], v2, s[24:25] offset:0
	global_load_dwordx4 v[110:113], v2, s[24:25] offset:1024
	global_load_dwordx4 v[114:117], v2, s[24:25] offset:2048
	global_load_dwordx4 v[118:121], v2, s[24:25] offset:3072
	global_load_dwordx4 v[122:125], v3, s[24:25] offset:0
	global_load_dwordx4 v[126:129], v3, s[24:25] offset:1024
	global_load_dwordx4 v[130:133], v3, s[24:25] offset:2048
	global_load_dwordx4 v[134:137], v3, s[24:25] offset:3072
	s_add_u32 s24, s24, 0x400000
	s_addc_u32 s25, s25, 0
	global_load_dwordx4 v[10:13], v2, s[24:25] offset:0
	global_load_dwordx4 v[14:17], v2, s[24:25] offset:1024
	global_load_dwordx4 v[18:21], v2, s[24:25] offset:2048
	global_load_dwordx4 v[22:25], v2, s[24:25] offset:3072
	global_load_dwordx4 v[26:29], v3, s[24:25] offset:0
	global_load_dwordx4 v[30:33], v3, s[24:25] offset:1024
	global_load_dwordx4 v[34:37], v3, s[24:25] offset:2048
	global_load_dwordx4 v[38:41], v3, s[24:25] offset:3072
	s_add_u32 s24, s24, 0x400000
	s_addc_u32 s25, s25, 0
	global_load_dwordx4 v[42:45], v2, s[24:25] offset:0
	global_load_dwordx4 v[46:49], v2, s[24:25] offset:1024
	global_load_dwordx4 v[50:53], v2, s[24:25] offset:2048
	global_load_dwordx4 v[54:57], v2, s[24:25] offset:3072
	global_load_dwordx4 v[58:61], v3, s[24:25] offset:0
	global_load_dwordx4 v[62:65], v3, s[24:25] offset:1024
	global_load_dwordx4 v[66:69], v3, s[24:25] offset:2048
	global_load_dwordx4 v[70:73], v3, s[24:25] offset:3072
	s_add_u32 s24, s24, 0x400000
	s_addc_u32 s25, s25, 0
	global_load_dwordx4 v[74:77], v2, s[24:25] offset:0
	global_load_dwordx4 v[78:81], v2, s[24:25] offset:1024
	global_load_dwordx4 v[82:85], v2, s[24:25] offset:2048
	global_load_dwordx4 v[86:89], v2, s[24:25] offset:3072
	global_load_dwordx4 v[90:93], v3, s[24:25] offset:0
	global_load_dwordx4 v[94:97], v3, s[24:25] offset:1024
	global_load_dwordx4 v[98:101], v3, s[24:25] offset:2048
	global_load_dwordx4 v[102:105], v3, s[24:25] offset:3072
	s_add_u32 s24, s24, 0x400000
	s_addc_u32 s25, s25, 0
	s_waitcnt vmcnt(16)
	v_pk_add_f32 v[106:107], v[106:107], v[10:11]
	v_pk_add_f32 v[108:109], v[108:109], v[12:13]
	v_pk_add_f32 v[110:111], v[110:111], v[14:15]
	v_pk_add_f32 v[112:113], v[112:113], v[16:17]
	v_pk_add_f32 v[114:115], v[114:115], v[18:19]
	v_pk_add_f32 v[116:117], v[116:117], v[20:21]
	v_pk_add_f32 v[118:119], v[118:119], v[22:23]
	v_pk_add_f32 v[120:121], v[120:121], v[24:25]
	v_pk_add_f32 v[122:123], v[122:123], v[26:27]
	v_pk_add_f32 v[124:125], v[124:125], v[28:29]
	v_pk_add_f32 v[126:127], v[126:127], v[30:31]
	v_pk_add_f32 v[128:129], v[128:129], v[32:33]
	v_pk_add_f32 v[130:131], v[130:131], v[34:35]
	v_pk_add_f32 v[132:133], v[132:133], v[36:37]
	v_pk_add_f32 v[134:135], v[134:135], v[38:39]
	v_pk_add_f32 v[136:137], v[136:137], v[40:41]
	global_load_dwordx4 v[10:13], v2, s[24:25] offset:0
	global_load_dwordx4 v[14:17], v2, s[24:25] offset:1024
	global_load_dwordx4 v[18:21], v2, s[24:25] offset:2048
	global_load_dwordx4 v[22:25], v2, s[24:25] offset:3072
	global_load_dwordx4 v[26:29], v3, s[24:25] offset:0
	global_load_dwordx4 v[30:33], v3, s[24:25] offset:1024
	global_load_dwordx4 v[34:37], v3, s[24:25] offset:2048
	global_load_dwordx4 v[38:41], v3, s[24:25] offset:3072
	s_add_u32 s24, s24, 0x400000
	s_addc_u32 s25, s25, 0
	s_waitcnt vmcnt(16)
	v_pk_add_f32 v[106:107], v[106:107], v[42:43]
	v_pk_add_f32 v[108:109], v[108:109], v[44:45]
	v_pk_add_f32 v[110:111], v[110:111], v[46:47]
	v_pk_add_f32 v[112:113], v[112:113], v[48:49]
	v_pk_add_f32 v[114:115], v[114:115], v[50:51]
	v_pk_add_f32 v[116:117], v[116:117], v[52:53]
	v_pk_add_f32 v[118:119], v[118:119], v[54:55]
	v_pk_add_f32 v[120:121], v[120:121], v[56:57]
	v_pk_add_f32 v[122:123], v[122:123], v[58:59]
	v_pk_add_f32 v[124:125], v[124:125], v[60:61]
	v_pk_add_f32 v[126:127], v[126:127], v[62:63]
	v_pk_add_f32 v[128:129], v[128:129], v[64:65]
	v_pk_add_f32 v[130:131], v[130:131], v[66:67]
	v_pk_add_f32 v[132:133], v[132:133], v[68:69]
	v_pk_add_f32 v[134:135], v[134:135], v[70:71]
	v_pk_add_f32 v[136:137], v[136:137], v[72:73]
	global_load_dwordx4 v[42:45], v2, s[24:25] offset:0
	global_load_dwordx4 v[46:49], v2, s[24:25] offset:1024
	global_load_dwordx4 v[50:53], v2, s[24:25] offset:2048
	global_load_dwordx4 v[54:57], v2, s[24:25] offset:3072
	global_load_dwordx4 v[58:61], v3, s[24:25] offset:0
	global_load_dwordx4 v[62:65], v3, s[24:25] offset:1024
	global_load_dwordx4 v[66:69], v3, s[24:25] offset:2048
	global_load_dwordx4 v[70:73], v3, s[24:25] offset:3072
	s_add_u32 s24, s24, 0x400000
	s_addc_u32 s25, s25, 0
	s_waitcnt vmcnt(16)
; __global__ void __launch_bounds__(512, 2) mega_fwd(Args a) {
;     ...
;         else { v[j] = (f32x4){0.f, 0.f, 0.f, 0.f};
; #pragma unroll
;           for (int ks = 0; ks < 16; ++ks) v[j] += *(const f32x4*)(PART + ((size_t)ks * MSAMP + (m - MP)) * DM + 4 * (64 * j + lane)); }
;         ss += (v[j].x * v[j].x + v[j].y * v[j].y) + (v[j].z * v[j].z + v[j].w * v[j].w); }
	v_pk_add_f32 v[106:107], v[106:107], v[74:75]
	v_pk_add_f32 v[108:109], v[108:109], v[76:77]
	v_pk_add_f32 v[110:111], v[110:111], v[78:79]
	v_pk_add_f32 v[112:113], v[112:113], v[80:81]
	v_pk_add_f32 v[114:115], v[114:115], v[82:83]
	v_pk_add_f32 v[116:117], v[116:117], v[84:85]
	v_pk_add_f32 v[118:119], v[118:119], v[86:87]
	v_pk_add_f32 v[120:121], v[120:121], v[88:89]
	v_pk_add_f32 v[122:123], v[122:123], v[90:91]
	v_pk_add_f32 v[124:125], v[124:125], v[92:93]
	v_pk_add_f32 v[126:127], v[126:127], v[94:95]
	v_pk_add_f32 v[128:129], v[128:129], v[96:97]
	v_pk_add_f32 v[130:131], v[130:131], v[98:99]
	v_pk_add_f32 v[132:133], v[132:133], v[100:101]
	v_pk_add_f32 v[134:135], v[134:135], v[102:103]
	v_pk_add_f32 v[136:137], v[136:137], v[104:105]
	global_load_dwordx4 v[74:77], v2, s[24:25] offset:0
	global_load_dwordx4 v[78:81], v2, s[24:25] offset:1024
	global_load_dwordx4 v[82:85], v2, s[24:25] offset:2048
	global_load_dwordx4 v[86:89], v2, s[24:25] offset:3072
	global_load_dwordx4 v[90:93], v3, s[24:25] offset:0
	global_load_dwordx4 v[94:97], v3, s[24:25] offset:1024
	global_load_dwordx4 v[98:101], v3, s[24:25] offset:2048
	global_load_dwordx4 v[102:105], v3, s[24:25] offset:3072
	s_add_u32 s24, s24, 0x400000
	s_addc_u32 s25, s25, 0
	s_waitcnt vmcnt(16)
	v_pk_add_f32 v[106:107], v[106:107], v[10:11]
	v_pk_add_f32 v[108:109], v[108:109], v[12:13]
	v_pk_add_f32 v[110:111], v[110:111], v[14:15]
	v_pk_add_f32 v[112:113], v[112:113], v[16:17]
	v_pk_add_f32 v[114:115], v[114:115], v[18:19]
	v_pk_add_f32 v[116:117], v[116:117], v[20:21]
	v_pk_add_f32 v[118:119], v[118:119], v[22:23]
	v_pk_add_f32 v[120:121], v[120:121], v[24:25]
	v_pk_add_f32 v[122:123], v[122:123], v[26:27]
	v_pk_add_f32 v[124:125], v[124:125], v[28:29]
	v_pk_add_f32 v[126:127], v[126:127], v[30:31]
	v_pk_add_f32 v[128:129], v[128:129], v[32:33]
	v_pk_add_f32 v[130:131], v[130:131], v[34:35]
	v_pk_add_f32 v[132:133], v[132:133], v[36:37]
	v_pk_add_f32 v[134:135], v[134:135], v[38:39]
	v_pk_add_f32 v[136:137], v[136:137], v[40:41]
	global_load_dwordx4 v[10:13], v2, s[24:25] offset:0
	global_load_dwordx4 v[14:17], v2, s[24:25] offset:1024
	global_load_dwordx4 v[18:21], v2, s[24:25] offset:2048
	global_load_dwordx4 v[22:25], v2, s[24:25] offset:3072
	global_load_dwordx4 v[26:29], v3, s[24:25] offset:0
	global_load_dwordx4 v[30:33], v3, s[24:25] offset:1024
	global_load_dwordx4 v[34:37], v3, s[24:25] offset:2048
	global_load_dwordx4 v[38:41], v3, s[24:25] offset:3072
	s_add_u32 s24, s24, 0x400000
	s_addc_u32 s25, s25, 0
	s_waitcnt vmcnt(16)
	v_pk_add_f32 v[106:107], v[106:107], v[42:43]
	v_pk_add_f32 v[108:109], v[108:109], v[44:45]
	v_pk_add_f32 v[110:111], v[110:111], v[46:47]
	v_pk_add_f32 v[112:113], v[112:113], v[48:49]
	v_pk_add_f32 v[114:115], v[114:115], v[50:51]
	v_pk_add_f32 v[116:117], v[116:117], v[52:53]
	v_pk_add_f32 v[118:119], v[118:119], v[54:55]
	v_pk_add_f32 v[120:121], v[120:121], v[56:57]
	v_pk_add_f32 v[122:123], v[122:123], v[58:59]
	v_pk_add_f32 v[124:125], v[124:125], v[60:61]
	v_pk_add_f32 v[126:127], v[126:127], v[62:63]
	v_pk_add_f32 v[128:129], v[128:129], v[64:65]
	v_pk_add_f32 v[130:131], v[130:131], v[66:67]
	v_pk_add_f32 v[132:133], v[132:133], v[68:69]
	v_pk_add_f32 v[134:135], v[134:135], v[70:71]
	v_pk_add_f32 v[136:137], v[136:137], v[72:73]
	global_load_dwordx4 v[42:45], v2, s[24:25] offset:0
	global_load_dwordx4 v[46:49], v2, s[24:25] offset:1024
	global_load_dwordx4 v[50:53], v2, s[24:25] offset:2048
	global_load_dwordx4 v[54:57], v2, s[24:25] offset:3072
	global_load_dwordx4 v[58:61], v3, s[24:25] offset:0
	global_load_dwordx4 v[62:65], v3, s[24:25] offset:1024
	global_load_dwordx4 v[66:69], v3, s[24:25] offset:2048
	global_load_dwordx4 v[70:73], v3, s[24:25] offset:3072
	s_add_u32 s24, s24, 0x400000
	s_addc_u32 s25, s25, 0
	s_waitcnt vmcnt(16)
	v_pk_add_f32 v[106:107], v[106:107], v[74:75]
	v_pk_add_f32 v[108:109], v[108:109], v[76:77]
	v_pk_add_f32 v[110:111], v[110:111], v[78:79]
	v_pk_add_f32 v[112:113], v[112:113], v[80:81]
	v_pk_add_f32 v[114:115], v[114:115], v[82:83]
	v_pk_add_f32 v[116:117], v[116:117], v[84:85]
	v_pk_add_f32 v[118:119], v[118:119], v[86:87]
	v_pk_add_f32 v[120:121], v[120:121], v[88:89]
	v_pk_add_f32 v[122:123], v[122:123], v[90:91]
	v_pk_add_f32 v[124:125], v[124:125], v[92:93]
	v_pk_add_f32 v[126:127], v[126:127], v[94:95]
	v_pk_add_f32 v[128:129], v[128:129], v[96:97]
	v_pk_add_f32 v[130:131], v[130:131], v[98:99]
	v_pk_add_f32 v[132:133], v[132:133], v[100:101]
	v_pk_add_f32 v[134:135], v[134:135], v[102:103]
	v_pk_add_f32 v[136:137], v[136:137], v[104:105]
	global_load_dwordx4 v[74:77], v2, s[24:25] offset:0
	global_load_dwordx4 v[78:81], v2, s[24:25] offset:1024
	global_load_dwordx4 v[82:85], v2, s[24:25] offset:2048
	global_load_dwordx4 v[86:89], v2, s[24:25] offset:3072
	global_load_dwordx4 v[90:93], v3, s[24:25] offset:0
	global_load_dwordx4 v[94:97], v3, s[24:25] offset:1024
	global_load_dwordx4 v[98:101], v3, s[24:25] offset:2048
	global_load_dwordx4 v[102:105], v3, s[24:25] offset:3072
	s_add_u32 s24, s24, 0x400000
	s_addc_u32 s25, s25, 0
	s_waitcnt vmcnt(16)
; __global__ void __launch_bounds__(512, 2) mega_fwd(Args a) {
;     ...
;         else { v[j] = (f32x4){0.f, 0.f, 0.f, 0.f};
; #pragma unroll
;           for (int ks = 0; ks < 16; ++ks) v[j] += *(const f32x4*)(PART + ((size_t)ks * MSAMP + (m - MP)) * DM + 4 * (64 * j + lane)); }
;         ss += (v[j].x * v[j].x + v[j].y * v[j].y) + (v[j].z * v[j].z + v[j].w * v[j].w); }
	v_pk_add_f32 v[106:107], v[106:107], v[10:11]
	v_pk_add_f32 v[108:109], v[108:109], v[12:13]
	v_pk_add_f32 v[110:111], v[110:111], v[14:15]
	v_pk_add_f32 v[112:113], v[112:113], v[16:17]
	v_pk_add_f32 v[114:115], v[114:115], v[18:19]
	v_pk_add_f32 v[116:117], v[116:117], v[20:21]
	v_pk_add_f32 v[118:119], v[118:119], v[22:23]
	v_pk_add_f32 v[120:121], v[120:121], v[24:25]
	v_pk_add_f32 v[122:123], v[122:123], v[26:27]
	v_pk_add_f32 v[124:125], v[124:125], v[28:29]
	v_pk_add_f32 v[126:127], v[126:127], v[30:31]
	v_pk_add_f32 v[128:129], v[128:129], v[32:33]
	v_pk_add_f32 v[130:131], v[130:131], v[34:35]
	v_pk_add_f32 v[132:133], v[132:133], v[36:37]
	v_pk_add_f32 v[134:135], v[134:135], v[38:39]
	v_pk_add_f32 v[136:137], v[136:137], v[40:41]
	global_load_dwordx4 v[10:13], v2, s[24:25] offset:0
	global_load_dwordx4 v[14:17], v2, s[24:25] offset:1024
	global_load_dwordx4 v[18:21], v2, s[24:25] offset:2048
	global_load_dwordx4 v[22:25], v2, s[24:25] offset:3072
	global_load_dwordx4 v[26:29], v3, s[24:25] offset:0
	global_load_dwordx4 v[30:33], v3, s[24:25] offset:1024
	global_load_dwordx4 v[34:37], v3, s[24:25] offset:2048
	global_load_dwordx4 v[38:41], v3, s[24:25] offset:3072
	s_add_u32 s24, s24, 0x400000
	s_addc_u32 s25, s25, 0
	s_waitcnt vmcnt(16)
	v_pk_add_f32 v[106:107], v[106:107], v[42:43]
	v_pk_add_f32 v[108:109], v[108:109], v[44:45]
	v_pk_add_f32 v[110:111], v[110:111], v[46:47]
	v_pk_add_f32 v[112:113], v[112:113], v[48:49]
	v_pk_add_f32 v[114:115], v[114:115], v[50:51]
	v_pk_add_f32 v[116:117], v[116:117], v[52:53]
	v_pk_add_f32 v[118:119], v[118:119], v[54:55]
	v_pk_add_f32 v[120:121], v[120:121], v[56:57]
	v_pk_add_f32 v[122:123], v[122:123], v[58:59]
	v_pk_add_f32 v[124:125], v[124:125], v[60:61]
	v_pk_add_f32 v[126:127], v[126:127], v[62:63]
	v_pk_add_f32 v[128:129], v[128:129], v[64:65]
	v_pk_add_f32 v[130:131], v[130:131], v[66:67]
	v_pk_add_f32 v[132:133], v[132:133], v[68:69]
	v_pk_add_f32 v[134:135], v[134:135], v[70:71]
	v_pk_add_f32 v[136:137], v[136:137], v[72:73]
	global_load_dwordx4 v[42:45], v2, s[24:25] offset:0
	global_load_dwordx4 v[46:49], v2, s[24:25] offset:1024
	global_load_dwordx4 v[50:53], v2, s[24:25] offset:2048
	global_load_dwordx4 v[54:57], v2, s[24:25] offset:3072
	global_load_dwordx4 v[58:61], v3, s[24:25] offset:0
	global_load_dwordx4 v[62:65], v3, s[24:25] offset:1024
	global_load_dwordx4 v[66:69], v3, s[24:25] offset:2048
	global_load_dwordx4 v[70:73], v3, s[24:25] offset:3072
	s_add_u32 s24, s24, 0x400000
	s_addc_u32 s25, s25, 0
	s_waitcnt vmcnt(16)
	v_pk_add_f32 v[106:107], v[106:107], v[74:75]
	v_pk_add_f32 v[108:109], v[108:109], v[76:77]
	v_pk_add_f32 v[110:111], v[110:111], v[78:79]
	v_pk_add_f32 v[112:113], v[112:113], v[80:81]
	v_pk_add_f32 v[114:115], v[114:115], v[82:83]
	v_pk_add_f32 v[116:117], v[116:117], v[84:85]
	v_pk_add_f32 v[118:119], v[118:119], v[86:87]
	v_pk_add_f32 v[120:121], v[120:121], v[88:89]
	v_pk_add_f32 v[122:123], v[122:123], v[90:91]
	v_pk_add_f32 v[124:125], v[124:125], v[92:93]
	v_pk_add_f32 v[126:127], v[126:127], v[94:95]
	v_pk_add_f32 v[128:129], v[128:129], v[96:97]
	v_pk_add_f32 v[130:131], v[130:131], v[98:99]
	v_pk_add_f32 v[132:133], v[132:133], v[100:101]
	v_pk_add_f32 v[134:135], v[134:135], v[102:103]
	v_pk_add_f32 v[136:137], v[136:137], v[104:105]
	global_load_dwordx4 v[74:77], v2, s[24:25] offset:0
	global_load_dwordx4 v[78:81], v2, s[24:25] offset:1024
	global_load_dwordx4 v[82:85], v2, s[24:25] offset:2048
	global_load_dwordx4 v[86:89], v2, s[24:25] offset:3072
	global_load_dwordx4 v[90:93], v3, s[24:25] offset:0
	global_load_dwordx4 v[94:97], v3, s[24:25] offset:1024
	global_load_dwordx4 v[98:101], v3, s[24:25] offset:2048
	global_load_dwordx4 v[102:105], v3, s[24:25] offset:3072
	s_add_u32 s24, s24, 0x400000
	s_addc_u32 s25, s25, 0
	s_waitcnt vmcnt(16)
	v_pk_add_f32 v[106:107], v[106:107], v[10:11]
	v_pk_add_f32 v[108:109], v[108:109], v[12:13]
	v_pk_add_f32 v[110:111], v[110:111], v[14:15]
	v_pk_add_f32 v[112:113], v[112:113], v[16:17]
	v_pk_add_f32 v[114:115], v[114:115], v[18:19]
	v_pk_add_f32 v[116:117], v[116:117], v[20:21]
	v_pk_add_f32 v[118:119], v[118:119], v[22:23]
	v_pk_add_f32 v[120:121], v[120:121], v[24:25]
	v_pk_add_f32 v[122:123], v[122:123], v[26:27]
	v_pk_add_f32 v[124:125], v[124:125], v[28:29]
	v_pk_add_f32 v[126:127], v[126:127], v[30:31]
	v_pk_add_f32 v[128:129], v[128:129], v[32:33]
	v_pk_add_f32 v[130:131], v[130:131], v[34:35]
	v_pk_add_f32 v[132:133], v[132:133], v[36:37]
	v_pk_add_f32 v[134:135], v[134:135], v[38:39]
	v_pk_add_f32 v[136:137], v[136:137], v[40:41]
	global_load_dwordx4 v[10:13], v2, s[24:25] offset:0
	global_load_dwordx4 v[14:17], v2, s[24:25] offset:1024
	global_load_dwordx4 v[18:21], v2, s[24:25] offset:2048
	global_load_dwordx4 v[22:25], v2, s[24:25] offset:3072
	global_load_dwordx4 v[26:29], v3, s[24:25] offset:0
	global_load_dwordx4 v[30:33], v3, s[24:25] offset:1024
	global_load_dwordx4 v[34:37], v3, s[24:25] offset:2048
	global_load_dwordx4 v[38:41], v3, s[24:25] offset:3072
	s_add_u32 s24, s24, 0x400000
	s_addc_u32 s25, s25, 0
	s_waitcnt vmcnt(16)
; __device__ __forceinline__ float bflo(unsigned w) { return __uint_as_float(w << 16); }
; __device__ __forceinline__ float bfhi(unsigned w) { return __uint_as_float(w & 0xffff0000u); }
; __global__ void __launch_bounds__(512, 2) mega_fwd(Args a) {
;     ...
;       for (int j = 0; j < 8; ++j) hin[j] = *(const f32x4*)(out + O_Y + (size_t)m * DM + 4 * (64 * j + lane));
;       f32x4 v[8]; float ss = 0.f;
; #pragma unroll
;       for (int j = 0; j < 8; ++j) {
;         if (m < MP) { const u32x2 w = *(const u32x2*)(MO + (size_t)m * DM + 4 * (64 * j + lane)); v[j] = (f32x4){bflo(w.x), bfhi(w.x), bflo(w.y), bfhi(w.y)}; }
;         else { v[j] = (f32x4){0.f, 0.f, 0.f, 0.f};
; #pragma unroll
;           for (int ks = 0; ks < 16; ++ks) v[j] += *(const f32x4*)(PART + ((size_t)ks * MSAMP + (m - MP)) * DM + 4 * (64 * j + lane)); }
;         ss += (v[j].x * v[j].x + v[j].y * v[j].y) + (v[j].z * v[j].z + v[j].w * v[j].w); }
;       const float r = rsqrtf(wave_sum(ss) * (1.f / DM) + EPS);
; #pragma unroll
;       for (int j = 0; j < 8; ++j) { const f32x4 gn = *(const f32x4*)(g2 + 4 * (64 * j + lane)); float* yp = out + O_Y + (size_t)m * DM + 4 * (64 * j + lane);
	v_pk_add_f32 v[106:107], v[106:107], v[42:43]
	v_pk_add_f32 v[108:109], v[108:109], v[44:45]
	v_pk_add_f32 v[110:111], v[110:111], v[46:47]
	v_pk_add_f32 v[112:113], v[112:113], v[48:49]
	v_pk_add_f32 v[114:115], v[114:115], v[50:51]
	v_pk_add_f32 v[116:117], v[116:117], v[52:53]
	v_pk_add_f32 v[118:119], v[118:119], v[54:55]
	v_pk_add_f32 v[120:121], v[120:121], v[56:57]
	v_pk_add_f32 v[122:123], v[122:123], v[58:59]
	v_pk_add_f32 v[124:125], v[124:125], v[60:61]
	v_pk_add_f32 v[126:127], v[126:127], v[62:63]
	v_pk_add_f32 v[128:129], v[128:129], v[64:65]
	v_pk_add_f32 v[130:131], v[130:131], v[66:67]
	v_pk_add_f32 v[132:133], v[132:133], v[68:69]
	v_pk_add_f32 v[134:135], v[134:135], v[70:71]
	v_pk_add_f32 v[136:137], v[136:137], v[72:73]
	global_load_dwordx4 v[42:45], v2, s[24:25] offset:0
	global_load_dwordx4 v[46:49], v2, s[24:25] offset:1024
	global_load_dwordx4 v[50:53], v2, s[24:25] offset:2048
	global_load_dwordx4 v[54:57], v2, s[24:25] offset:3072
	global_load_dwordx4 v[58:61], v3, s[24:25] offset:0
	global_load_dwordx4 v[62:65], v3, s[24:25] offset:1024
	global_load_dwordx4 v[66:69], v3, s[24:25] offset:2048
	global_load_dwordx4 v[70:73], v3, s[24:25] offset:3072
	s_add_u32 s24, s24, 0x400000
	s_addc_u32 s25, s25, 0
	s_waitcnt vmcnt(16)
	v_pk_add_f32 v[106:107], v[106:107], v[74:75]
	v_pk_add_f32 v[108:109], v[108:109], v[76:77]
	v_pk_add_f32 v[110:111], v[110:111], v[78:79]
	v_pk_add_f32 v[112:113], v[112:113], v[80:81]
	v_pk_add_f32 v[114:115], v[114:115], v[82:83]
	v_pk_add_f32 v[116:117], v[116:117], v[84:85]
	v_pk_add_f32 v[118:119], v[118:119], v[86:87]
	v_pk_add_f32 v[120:121], v[120:121], v[88:89]
	v_pk_add_f32 v[122:123], v[122:123], v[90:91]
	v_pk_add_f32 v[124:125], v[124:125], v[92:93]
	v_pk_add_f32 v[126:127], v[126:127], v[94:95]
	v_pk_add_f32 v[128:129], v[128:129], v[96:97]
	v_pk_add_f32 v[130:131], v[130:131], v[98:99]
	v_pk_add_f32 v[132:133], v[132:133], v[100:101]
	v_pk_add_f32 v[134:135], v[134:135], v[102:103]
	v_pk_add_f32 v[136:137], v[136:137], v[104:105]
	global_load_dwordx4 v[74:77], v2, s[24:25] offset:0
	global_load_dwordx4 v[78:81], v2, s[24:25] offset:1024
	global_load_dwordx4 v[82:85], v2, s[24:25] offset:2048
	global_load_dwordx4 v[86:89], v2, s[24:25] offset:3072
	global_load_dwordx4 v[90:93], v3, s[24:25] offset:0
	global_load_dwordx4 v[94:97], v3, s[24:25] offset:1024
	global_load_dwordx4 v[98:101], v3, s[24:25] offset:2048
	global_load_dwordx4 v[102:105], v3, s[24:25] offset:3072
	s_waitcnt vmcnt(16)
	v_pk_add_f32 v[106:107], v[106:107], v[10:11]
	v_pk_add_f32 v[108:109], v[108:109], v[12:13]
	v_pk_add_f32 v[110:111], v[110:111], v[14:15]
	v_pk_add_f32 v[112:113], v[112:113], v[16:17]
	v_pk_add_f32 v[114:115], v[114:115], v[18:19]
	v_pk_add_f32 v[116:117], v[116:117], v[20:21]
	v_pk_add_f32 v[118:119], v[118:119], v[22:23]
	v_pk_add_f32 v[120:121], v[120:121], v[24:25]
	v_pk_add_f32 v[122:123], v[122:123], v[26:27]
	v_pk_add_f32 v[124:125], v[124:125], v[28:29]
	v_pk_add_f32 v[126:127], v[126:127], v[30:31]
	v_pk_add_f32 v[128:129], v[128:129], v[32:33]
	v_pk_add_f32 v[130:131], v[130:131], v[34:35]
	v_pk_add_f32 v[132:133], v[132:133], v[36:37]
	v_pk_add_f32 v[134:135], v[134:135], v[38:39]
	v_pk_add_f32 v[136:137], v[136:137], v[40:41]
	s_waitcnt vmcnt(8)
	v_pk_add_f32 v[106:107], v[106:107], v[42:43]
	v_pk_add_f32 v[108:109], v[108:109], v[44:45]
	v_pk_add_f32 v[110:111], v[110:111], v[46:47]
	v_pk_add_f32 v[112:113], v[112:113], v[48:49]
	v_pk_add_f32 v[114:115], v[114:115], v[50:51]
	v_pk_add_f32 v[116:117], v[116:117], v[52:53]
	v_pk_add_f32 v[118:119], v[118:119], v[54:55]
	v_pk_add_f32 v[120:121], v[120:121], v[56:57]
	v_pk_add_f32 v[122:123], v[122:123], v[58:59]
	v_pk_add_f32 v[124:125], v[124:125], v[60:61]
	v_pk_add_f32 v[126:127], v[126:127], v[62:63]
	v_pk_add_f32 v[128:129], v[128:129], v[64:65]
	v_pk_add_f32 v[130:131], v[130:131], v[66:67]
	v_pk_add_f32 v[132:133], v[132:133], v[68:69]
	v_pk_add_f32 v[134:135], v[134:135], v[70:71]
	v_pk_add_f32 v[136:137], v[136:137], v[72:73]
	s_waitcnt vmcnt(0)
	v_pk_add_f32 v[106:107], v[106:107], v[74:75]
	v_pk_add_f32 v[108:109], v[108:109], v[76:77]
	v_pk_add_f32 v[110:111], v[110:111], v[78:79]
	v_pk_add_f32 v[112:113], v[112:113], v[80:81]
	v_pk_add_f32 v[114:115], v[114:115], v[82:83]
	v_pk_add_f32 v[116:117], v[116:117], v[84:85]
	v_pk_add_f32 v[118:119], v[118:119], v[86:87]
	v_pk_add_f32 v[120:121], v[120:121], v[88:89]
	v_pk_add_f32 v[122:123], v[122:123], v[90:91]
	v_pk_add_f32 v[124:125], v[124:125], v[92:93]
	v_pk_add_f32 v[126:127], v[126:127], v[94:95]
	v_pk_add_f32 v[128:129], v[128:129], v[96:97]
	v_pk_add_f32 v[130:131], v[130:131], v[98:99]
	v_pk_add_f32 v[132:133], v[132:133], v[100:101]
	v_pk_add_f32 v[134:135], v[134:135], v[102:103]
	v_pk_add_f32 v[136:137], v[136:137], v[104:105]
	s_add_u32 s97, s18, 0x4000
	s_lshl_b32 s34, s97, 13
	s_add_u32 s28, s8, s34
	s_addc_u32 s29, s9, 0
	global_load_dwordx4 v[74:77], v2, s[28:29] offset:0
	global_load_dwordx4 v[78:81], v2, s[28:29] offset:1024
	global_load_dwordx4 v[82:85], v2, s[28:29] offset:2048
	global_load_dwordx4 v[86:89], v2, s[28:29] offset:3072
	global_load_dwordx4 v[90:93], v3, s[28:29] offset:0
	global_load_dwordx4 v[94:97], v3, s[28:29] offset:1024
	global_load_dwordx4 v[98:101], v3, s[28:29] offset:2048
	global_load_dwordx4 v[102:105], v3, s[28:29] offset:3072
	global_load_dwordx4 v[10:13], v2, s[20:21] offset:0
	global_load_dwordx4 v[14:17], v2, s[20:21] offset:1024
	global_load_dwordx4 v[18:21], v2, s[20:21] offset:2048
	global_load_dwordx4 v[22:25], v2, s[20:21] offset:3072
	global_load_dwordx4 v[26:29], v3, s[20:21] offset:0
	global_load_dwordx4 v[30:33], v3, s[20:21] offset:1024
	global_load_dwordx4 v[34:37], v3, s[20:21] offset:2048
	global_load_dwordx4 v[38:41], v3, s[20:21] offset:3072
	s_waitcnt vmcnt(0)
; __global__ void __launch_bounds__(512, 2) mega_fwd(Args a) {
;     ...
;         ss += (v[j].x * v[j].x + v[j].y * v[j].y) + (v[j].z * v[j].z + v[j].w * v[j].w); }
;       const float r = rsqrtf(wave_sum(ss) * (1.f / DM) + EPS);
; #pragma unroll
;       for (int j = 0; j < 8; ++j) { const f32x4 gn = *(const f32x4*)(g2 + 4 * (64 * j + lane)); float* yp = out + O_Y + (size_t)m * DM + 4 * (64 * j + lane);
;         *(f32x4*)yp = hin[j] + v[j] * r * gn; }
	v_mov_b32_e32 v9, 0
	v_mul_f32_e32 v174, v106, v106
	v_fmac_f32_e32 v174, v107, v107
	v_mul_f32_e32 v175, v108, v108
	v_fmac_f32_e32 v175, v109, v109
	v_add_f32_e32 v174, v174, v175
	v_add_f32_e32 v9, v9, v174
	v_mul_f32_e32 v174, v110, v110
	v_fmac_f32_e32 v174, v111, v111
	v_mul_f32_e32 v175, v112, v112
	v_fmac_f32_e32 v175, v113, v113
	v_add_f32_e32 v174, v174, v175
	v_add_f32_e32 v9, v9, v174
	v_mul_f32_e32 v174, v114, v114
	v_fmac_f32_e32 v174, v115, v115
	v_mul_f32_e32 v175, v116, v116
	v_fmac_f32_e32 v175, v117, v117
	v_add_f32_e32 v174, v174, v175
	v_add_f32_e32 v9, v9, v174
	v_mul_f32_e32 v174, v118, v118
	v_fmac_f32_e32 v174, v119, v119
	v_mul_f32_e32 v175, v120, v120
	v_fmac_f32_e32 v175, v121, v121
	v_add_f32_e32 v174, v174, v175
	v_add_f32_e32 v9, v9, v174
	v_mul_f32_e32 v174, v122, v122
	v_fmac_f32_e32 v174, v123, v123
	v_mul_f32_e32 v175, v124, v124
	v_fmac_f32_e32 v175, v125, v125
	v_add_f32_e32 v174, v174, v175
	v_add_f32_e32 v9, v9, v174
	v_mul_f32_e32 v174, v126, v126
	v_fmac_f32_e32 v174, v127, v127
	v_mul_f32_e32 v175, v128, v128
	v_fmac_f32_e32 v175, v129, v129
	v_add_f32_e32 v174, v174, v175
	v_add_f32_e32 v9, v9, v174
	v_mul_f32_e32 v174, v130, v130
	v_fmac_f32_e32 v174, v131, v131
	v_mul_f32_e32 v175, v132, v132
	v_fmac_f32_e32 v175, v133, v133
	v_add_f32_e32 v174, v174, v175
	v_add_f32_e32 v9, v9, v174
	v_mul_f32_e32 v174, v134, v134
	v_fmac_f32_e32 v174, v135, v135
	v_mul_f32_e32 v175, v136, v136
	v_fmac_f32_e32 v175, v137, v137
	v_add_f32_e32 v174, v174, v175
	v_add_f32_e32 v9, v9, v174
	s_nop 1
	v_add_f32_dpp v9, v9, v9 quad_perm:[1,0,3,2] row_mask:0xf bank_mask:0xf
	s_nop 1
	v_add_f32_dpp v9, v9, v9 quad_perm:[2,3,0,1] row_mask:0xf bank_mask:0xf
	s_nop 1
	v_add_f32_dpp v9, v9, v9 row_half_mirror row_mask:0xf bank_mask:0xf
	s_nop 1
	v_add_f32_dpp v9, v9, v9 row_mirror row_mask:0xf bank_mask:0xf
	s_nop 1
	v_add_f32_dpp v9, v9, v9 row_bcast:15 row_mask:0xa bank_mask:0xf
	s_nop 1
	v_add_f32_dpp v9, v9, v9 row_bcast:31 row_mask:0xc bank_mask:0xf
	s_nop 1
	v_readlane_b32 s79, v9, 63
	s_nop 1
	v_mov_b32_e32 v174, s79
	v_fmamk_f32 v174, v174, 0x3a000000, v177
	v_rsq_f32_e32 v176, v174
	s_nop 0
	v_mul_f32_e32 v5, v106, v176
	v_mul_f32_e32 v6, v107, v176
	v_mul_f32_e32 v7, v108, v176
	v_mul_f32_e32 v8, v109, v176
	v_fmac_f32_e32 v74, v5, v10
	v_fmac_f32_e32 v75, v6, v11
	v_fmac_f32_e32 v76, v7, v12
	v_fmac_f32_e32 v77, v8, v13
	v_mul_f32_e32 v5, v110, v176
	v_mul_f32_e32 v6, v111, v176
	v_mul_f32_e32 v7, v112, v176
	v_mul_f32_e32 v8, v113, v176
	v_fmac_f32_e32 v78, v5, v14
	v_fmac_f32_e32 v79, v6, v15
	v_fmac_f32_e32 v80, v7, v16
	v_fmac_f32_e32 v81, v8, v17
	v_mul_f32_e32 v5, v114, v176
	v_mul_f32_e32 v6, v115, v176
	v_mul_f32_e32 v7, v116, v176
	v_mul_f32_e32 v8, v117, v176
	v_fmac_f32_e32 v82, v5, v18
	v_fmac_f32_e32 v83, v6, v19
	v_fmac_f32_e32 v84, v7, v20
	v_fmac_f32_e32 v85, v8, v21
	v_mul_f32_e32 v5, v118, v176
	v_mul_f32_e32 v6, v119, v176
	v_mul_f32_e32 v7, v120, v176
	v_mul_f32_e32 v8, v121, v176
	v_fmac_f32_e32 v86, v5, v22
	v_fmac_f32_e32 v87, v6, v23
	v_fmac_f32_e32 v88, v7, v24
	v_fmac_f32_e32 v89, v8, v25
	v_mul_f32_e32 v5, v122, v176
	v_mul_f32_e32 v6, v123, v176
	v_mul_f32_e32 v7, v124, v176
	v_mul_f32_e32 v8, v125, v176
	v_fmac_f32_e32 v90, v5, v26
	v_fmac_f32_e32 v91, v6, v27
	v_fmac_f32_e32 v92, v7, v28
	v_fmac_f32_e32 v93, v8, v29
	v_mul_f32_e32 v5, v126, v176
	v_mul_f32_e32 v6, v127, v176
	v_mul_f32_e32 v7, v128, v176
	v_mul_f32_e32 v8, v129, v176
	v_fmac_f32_e32 v94, v5, v30
	v_fmac_f32_e32 v95, v6, v31
	v_fmac_f32_e32 v96, v7, v32
	v_fmac_f32_e32 v97, v8, v33
	v_mul_f32_e32 v5, v130, v176
	v_mul_f32_e32 v6, v131, v176
	v_mul_f32_e32 v7, v132, v176
	v_mul_f32_e32 v8, v133, v176
	v_fmac_f32_e32 v98, v5, v34
	v_fmac_f32_e32 v99, v6, v35
	v_fmac_f32_e32 v100, v7, v36
	v_fmac_f32_e32 v101, v8, v37
	v_mul_f32_e32 v5, v134, v176
	v_mul_f32_e32 v6, v135, v176
	v_mul_f32_e32 v7, v136, v176
	v_mul_f32_e32 v8, v137, v176
	v_fmac_f32_e32 v102, v5, v38
	v_fmac_f32_e32 v103, v6, v39
	v_fmac_f32_e32 v104, v7, v40
	v_fmac_f32_e32 v105, v8, v41
	global_store_dwordx4 v2, v[74:77], s[28:29] offset:0
	global_store_dwordx4 v2, v[78:81], s[28:29] offset:1024
	global_store_dwordx4 v2, v[82:85], s[28:29] offset:2048
	global_store_dwordx4 v2, v[86:89], s[28:29] offset:3072
	global_store_dwordx4 v3, v[90:93], s[28:29] offset:0
	global_store_dwordx4 v3, v[94:97], s[28:29] offset:1024
	global_store_dwordx4 v3, v[98:101], s[28:29] offset:2048
	global_store_dwordx4 v3, v[102:105], s[28:29] offset:3072
	s_lshr_b32 s97, s78, 2
	s_add_u32 s18, s18, s97
	s_branch .Lew9_samp_loop
.Lew9_prompt:
	global_load_dwordx4 v[10:13], v2, s[20:21] offset:0
	global_load_dwordx4 v[14:17], v2, s[20:21] offset:1024
	global_load_dwordx4 v[18:21], v2, s[20:21] offset:2048
	global_load_dwordx4 v[22:25], v2, s[20:21] offset:3072
	global_load_dwordx4 v[26:29], v3, s[20:21] offset:0
	global_load_dwordx4 v[30:33], v3, s[20:21] offset:1024
	global_load_dwordx4 v[34:37], v3, s[20:21] offset:2048
	global_load_dwordx4 v[38:41], v3, s[20:21] offset:3072
	s_mov_b32 s18, s96
; __device__ __forceinline__ float bflo(unsigned w) { return __uint_as_float(w << 16); }
; __device__ __forceinline__ float bfhi(unsigned w) { return __uint_as_float(w & 0xffff0000u); }
; __global__ void __launch_bounds__(512, 2) mega_fwd(Args a) {
;     ...
;     for (int m = gw; m < MT; m += NGW) {
;       f32x4 hin[8];
; #pragma unroll
;       for (int j = 0; j < 8; ++j) hin[j] = *(const f32x4*)(out + O_Y + (size_t)m * DM + 4 * (64 * j + lane));
;       f32x4 v[8]; float ss = 0.f;
; #pragma unroll
;       for (int j = 0; j < 8; ++j) {
;         if (m < MP) { const u32x2 w = *(const u32x2*)(MO + (size_t)m * DM + 4 * (64 * j + lane)); v[j] = (f32x4){bflo(w.x), bfhi(w.x), bflo(w.y), bfhi(w.y)}; }
;         else { v[j] = (f32x4){0.f, 0.f, 0.f, 0.f};
; #pragma unroll
;           for (int ks = 0; ks < 16; ++ks) v[j] += *(const f32x4*)(PART + ((size_t)ks * MSAMP + (m - MP)) * DM + 4 * (64 * j + lane)); }
;         ss += (v[j].x * v[j].x + v[j].y * v[j].y) + (v[j].z * v[j].z + v[j].w * v[j].w); }
;       const float r = rsqrtf(wave_sum(ss) * (1.f / DM) + EPS);
.Lew9_loop:
	s_cmpk_ge_u32 s18, 0x4000
	s_cbranch_scc1 .Lew9_done
	s_add_u32 s19, s18, s78
	s_lshl_b32 s97, s18, 13
	s_add_u32 s24, s8, s97
	s_addc_u32 s25, s9, 0
	s_lshl_b32 s97, s18, 12
	s_add_u32 s26, s12, s97
	s_addc_u32 s27, s13, 0
	global_load_dwordx4 v[74:77], v2, s[24:25] offset:0
	global_load_dwordx4 v[78:81], v2, s[24:25] offset:1024
	global_load_dwordx4 v[82:85], v2, s[24:25] offset:2048
	global_load_dwordx4 v[86:89], v2, s[24:25] offset:3072
	global_load_dwordx4 v[90:93], v3, s[24:25] offset:0
	global_load_dwordx4 v[94:97], v3, s[24:25] offset:1024
	global_load_dwordx4 v[98:101], v3, s[24:25] offset:2048
	global_load_dwordx4 v[102:105], v3, s[24:25] offset:3072
	global_load_dwordx2 v[138:139], v4, s[26:27] offset:0
	global_load_dwordx2 v[140:141], v4, s[26:27] offset:512
	global_load_dwordx2 v[142:143], v4, s[26:27] offset:1024
	global_load_dwordx2 v[144:145], v4, s[26:27] offset:1536
	global_load_dwordx2 v[146:147], v4, s[26:27] offset:2048
	global_load_dwordx2 v[148:149], v4, s[26:27] offset:2560
	global_load_dwordx2 v[150:151], v4, s[26:27] offset:3072
	global_load_dwordx2 v[152:153], v4, s[26:27] offset:3584
	s_cmpk_ge_u32 s19, 0x4000
	s_cbranch_scc1 .Lew9_single
	s_lshl_b32 s97, s19, 13
	s_add_u32 s28, s8, s97
	s_addc_u32 s29, s9, 0
	s_lshl_b32 s97, s19, 12
	s_add_u32 s30, s12, s97
	s_addc_u32 s31, s13, 0
	global_load_dwordx4 v[106:109], v2, s[28:29] offset:0
	global_load_dwordx4 v[110:113], v2, s[28:29] offset:1024
	global_load_dwordx4 v[114:117], v2, s[28:29] offset:2048
	global_load_dwordx4 v[118:121], v2, s[28:29] offset:3072
	global_load_dwordx4 v[122:125], v3, s[28:29] offset:0
	global_load_dwordx4 v[126:129], v3, s[28:29] offset:1024
	global_load_dwordx4 v[130:133], v3, s[28:29] offset:2048
	global_load_dwordx4 v[134:137], v3, s[28:29] offset:3072
	global_load_dwordx2 v[154:155], v4, s[30:31] offset:0
	global_load_dwordx2 v[156:157], v4, s[30:31] offset:512
	global_load_dwordx2 v[158:159], v4, s[30:31] offset:1024
	global_load_dwordx2 v[160:161], v4, s[30:31] offset:1536
	global_load_dwordx2 v[162:163], v4, s[30:31] offset:2048
	global_load_dwordx2 v[166:167], v4, s[30:31] offset:2560
	global_load_dwordx2 v[168:169], v4, s[30:31] offset:3072
	global_load_dwordx2 v[172:173], v4, s[30:31] offset:3584
	s_waitcnt vmcnt(16)
	v_mov_b32_e32 v9, 0
	v_lshlrev_b32_e32 v5, 16, v138
	v_and_b32_e32 v6, 0xffff0000, v138
	v_lshlrev_b32_e32 v7, 16, v139
	v_and_b32_e32 v8, 0xffff0000, v139
	v_mul_f32_e32 v174, v5, v5
	v_fmac_f32_e32 v174, v6, v6
	v_mul_f32_e32 v175, v7, v7
	v_fmac_f32_e32 v175, v8, v8
	v_add_f32_e32 v174, v174, v175
	v_add_f32_e32 v9, v9, v174
	v_lshlrev_b32_e32 v5, 16, v140
	v_and_b32_e32 v6, 0xffff0000, v140
	v_lshlrev_b32_e32 v7, 16, v141
	v_and_b32_e32 v8, 0xffff0000, v141
	v_mul_f32_e32 v174, v5, v5
	v_fmac_f32_e32 v174, v6, v6
	v_mul_f32_e32 v175, v7, v7
	v_fmac_f32_e32 v175, v8, v8
	v_add_f32_e32 v174, v174, v175
	v_add_f32_e32 v9, v9, v174
	v_lshlrev_b32_e32 v5, 16, v142
	v_and_b32_e32 v6, 0xffff0000, v142
	v_lshlrev_b32_e32 v7, 16, v143
	v_and_b32_e32 v8, 0xffff0000, v143
	v_mul_f32_e32 v174, v5, v5
	v_fmac_f32_e32 v174, v6, v6
	v_mul_f32_e32 v175, v7, v7
	v_fmac_f32_e32 v175, v8, v8
	v_add_f32_e32 v174, v174, v175
	v_add_f32_e32 v9, v9, v174
	v_lshlrev_b32_e32 v5, 16, v144
	v_and_b32_e32 v6, 0xffff0000, v144
	v_lshlrev_b32_e32 v7, 16, v145
	v_and_b32_e32 v8, 0xffff0000, v145
	v_mul_f32_e32 v174, v5, v5
	v_fmac_f32_e32 v174, v6, v6
	v_mul_f32_e32 v175, v7, v7
	v_fmac_f32_e32 v175, v8, v8
	v_add_f32_e32 v174, v174, v175
	v_add_f32_e32 v9, v9, v174
	v_lshlrev_b32_e32 v5, 16, v146
	v_and_b32_e32 v6, 0xffff0000, v146
	v_lshlrev_b32_e32 v7, 16, v147
	v_and_b32_e32 v8, 0xffff0000, v147
	v_mul_f32_e32 v174, v5, v5
	v_fmac_f32_e32 v174, v6, v6
	v_mul_f32_e32 v175, v7, v7
	v_fmac_f32_e32 v175, v8, v8
	v_add_f32_e32 v174, v174, v175
	v_add_f32_e32 v9, v9, v174
	v_lshlrev_b32_e32 v5, 16, v148
	v_and_b32_e32 v6, 0xffff0000, v148
	v_lshlrev_b32_e32 v7, 16, v149
	v_and_b32_e32 v8, 0xffff0000, v149
	v_mul_f32_e32 v174, v5, v5
	v_fmac_f32_e32 v174, v6, v6
	v_mul_f32_e32 v175, v7, v7
	v_fmac_f32_e32 v175, v8, v8
	v_add_f32_e32 v174, v174, v175
	v_add_f32_e32 v9, v9, v174
	v_lshlrev_b32_e32 v5, 16, v150
	v_and_b32_e32 v6, 0xffff0000, v150
	v_lshlrev_b32_e32 v7, 16, v151
	v_and_b32_e32 v8, 0xffff0000, v151
	v_mul_f32_e32 v174, v5, v5
	v_fmac_f32_e32 v174, v6, v6
	v_mul_f32_e32 v175, v7, v7
	v_fmac_f32_e32 v175, v8, v8
	v_add_f32_e32 v174, v174, v175
	v_add_f32_e32 v9, v9, v174
	v_lshlrev_b32_e32 v5, 16, v152
	v_and_b32_e32 v6, 0xffff0000, v152
	v_lshlrev_b32_e32 v7, 16, v153
	v_and_b32_e32 v8, 0xffff0000, v153
	v_mul_f32_e32 v174, v5, v5
	v_fmac_f32_e32 v174, v6, v6
	v_mul_f32_e32 v175, v7, v7
	v_fmac_f32_e32 v175, v8, v8
	v_add_f32_e32 v174, v174, v175
	v_add_f32_e32 v9, v9, v174
	s_nop 1
	v_add_f32_dpp v9, v9, v9 quad_perm:[1,0,3,2] row_mask:0xf bank_mask:0xf
	s_nop 1
	v_add_f32_dpp v9, v9, v9 quad_perm:[2,3,0,1] row_mask:0xf bank_mask:0xf
	s_nop 1
	v_add_f32_dpp v9, v9, v9 row_half_mirror row_mask:0xf bank_mask:0xf
	s_nop 1
	v_add_f32_dpp v9, v9, v9 row_mirror row_mask:0xf bank_mask:0xf
	s_nop 1
	v_add_f32_dpp v9, v9, v9 row_bcast:15 row_mask:0xa bank_mask:0xf
	s_nop 1
	v_add_f32_dpp v9, v9, v9 row_bcast:31 row_mask:0xc bank_mask:0xf
	s_nop 1
	v_readlane_b32 s79, v9, 63
	s_nop 1
	v_mov_b32_e32 v174, s79
	v_fmamk_f32 v174, v174, 0x3a000000, v177
	v_rsq_f32_e32 v176, v174
	s_nop 0
	v_lshlrev_b32_e32 v5, 16, v138
	v_and_b32_e32 v6, 0xffff0000, v138
	v_lshlrev_b32_e32 v7, 16, v139
	v_and_b32_e32 v8, 0xffff0000, v139
	v_mul_f32_e32 v5, v5, v176
	v_mul_f32_e32 v6, v6, v176
	v_mul_f32_e32 v7, v7, v176
	v_mul_f32_e32 v8, v8, v176
; __device__ __forceinline__ float bflo(unsigned w) { return __uint_as_float(w << 16); }
; __device__ __forceinline__ float bfhi(unsigned w) { return __uint_as_float(w & 0xffff0000u); }
; __global__ void __launch_bounds__(512, 2) mega_fwd(Args a) {
;     ...
;         if (m < MP) { const u32x2 w = *(const u32x2*)(MO + (size_t)m * DM + 4 * (64 * j + lane)); v[j] = (f32x4){bflo(w.x), bfhi(w.x), bflo(w.y), bfhi(w.y)}; }
;         else { v[j] = (f32x4){0.f, 0.f, 0.f, 0.f};
; #pragma unroll
;           for (int ks = 0; ks < 16; ++ks) v[j] += *(const f32x4*)(PART + ((size_t)ks * MSAMP + (m - MP)) * DM + 4 * (64 * j + lane)); }
;         ss += (v[j].x * v[j].x + v[j].y * v[j].y) + (v[j].z * v[j].z + v[j].w * v[j].w); }
;       const float r = rsqrtf(wave_sum(ss) * (1.f / DM) + EPS);
; #pragma unroll
;       for (int j = 0; j < 8; ++j) { const f32x4 gn = *(const f32x4*)(g2 + 4 * (64 * j + lane)); float* yp = out + O_Y + (size_t)m * DM + 4 * (64 * j + lane);
;         *(f32x4*)yp = hin[j] + v[j] * r * gn; }
	v_fmac_f32_e32 v74, v5, v10
	v_fmac_f32_e32 v75, v6, v11
	v_fmac_f32_e32 v76, v7, v12
	v_fmac_f32_e32 v77, v8, v13
	v_lshlrev_b32_e32 v5, 16, v140
	v_and_b32_e32 v6, 0xffff0000, v140
	v_lshlrev_b32_e32 v7, 16, v141
	v_and_b32_e32 v8, 0xffff0000, v141
	v_mul_f32_e32 v5, v5, v176
	v_mul_f32_e32 v6, v6, v176
	v_mul_f32_e32 v7, v7, v176
	v_mul_f32_e32 v8, v8, v176
	v_fmac_f32_e32 v78, v5, v14
	v_fmac_f32_e32 v79, v6, v15
	v_fmac_f32_e32 v80, v7, v16
	v_fmac_f32_e32 v81, v8, v17
	v_lshlrev_b32_e32 v5, 16, v142
	v_and_b32_e32 v6, 0xffff0000, v142
	v_lshlrev_b32_e32 v7, 16, v143
	v_and_b32_e32 v8, 0xffff0000, v143
	v_mul_f32_e32 v5, v5, v176
	v_mul_f32_e32 v6, v6, v176
	v_mul_f32_e32 v7, v7, v176
	v_mul_f32_e32 v8, v8, v176
	v_fmac_f32_e32 v82, v5, v18
	v_fmac_f32_e32 v83, v6, v19
	v_fmac_f32_e32 v84, v7, v20
	v_fmac_f32_e32 v85, v8, v21
	v_lshlrev_b32_e32 v5, 16, v144
	v_and_b32_e32 v6, 0xffff0000, v144
	v_lshlrev_b32_e32 v7, 16, v145
	v_and_b32_e32 v8, 0xffff0000, v145
	v_mul_f32_e32 v5, v5, v176
	v_mul_f32_e32 v6, v6, v176
	v_mul_f32_e32 v7, v7, v176
	v_mul_f32_e32 v8, v8, v176
	v_fmac_f32_e32 v86, v5, v22
	v_fmac_f32_e32 v87, v6, v23
	v_fmac_f32_e32 v88, v7, v24
	v_fmac_f32_e32 v89, v8, v25
	v_lshlrev_b32_e32 v5, 16, v146
	v_and_b32_e32 v6, 0xffff0000, v146
	v_lshlrev_b32_e32 v7, 16, v147
	v_and_b32_e32 v8, 0xffff0000, v147
	v_mul_f32_e32 v5, v5, v176
	v_mul_f32_e32 v6, v6, v176
	v_mul_f32_e32 v7, v7, v176
	v_mul_f32_e32 v8, v8, v176
	v_fmac_f32_e32 v90, v5, v26
	v_fmac_f32_e32 v91, v6, v27
	v_fmac_f32_e32 v92, v7, v28
	v_fmac_f32_e32 v93, v8, v29
	v_lshlrev_b32_e32 v5, 16, v148
	v_and_b32_e32 v6, 0xffff0000, v148
	v_lshlrev_b32_e32 v7, 16, v149
	v_and_b32_e32 v8, 0xffff0000, v149
	v_mul_f32_e32 v5, v5, v176
	v_mul_f32_e32 v6, v6, v176
	v_mul_f32_e32 v7, v7, v176
	v_mul_f32_e32 v8, v8, v176
	v_fmac_f32_e32 v94, v5, v30
	v_fmac_f32_e32 v95, v6, v31
	v_fmac_f32_e32 v96, v7, v32
	v_fmac_f32_e32 v97, v8, v33
	v_lshlrev_b32_e32 v5, 16, v150
	v_and_b32_e32 v6, 0xffff0000, v150
	v_lshlrev_b32_e32 v7, 16, v151
	v_and_b32_e32 v8, 0xffff0000, v151
	v_mul_f32_e32 v5, v5, v176
	v_mul_f32_e32 v6, v6, v176
	v_mul_f32_e32 v7, v7, v176
	v_mul_f32_e32 v8, v8, v176
	v_fmac_f32_e32 v98, v5, v34
	v_fmac_f32_e32 v99, v6, v35
	v_fmac_f32_e32 v100, v7, v36
	v_fmac_f32_e32 v101, v8, v37
	v_lshlrev_b32_e32 v5, 16, v152
	v_and_b32_e32 v6, 0xffff0000, v152
	v_lshlrev_b32_e32 v7, 16, v153
	v_and_b32_e32 v8, 0xffff0000, v153
	v_mul_f32_e32 v5, v5, v176
	v_mul_f32_e32 v6, v6, v176
	v_mul_f32_e32 v7, v7, v176
	v_mul_f32_e32 v8, v8, v176
	v_fmac_f32_e32 v102, v5, v38
	v_fmac_f32_e32 v103, v6, v39
	v_fmac_f32_e32 v104, v7, v40
	v_fmac_f32_e32 v105, v8, v41
	global_store_dwordx4 v2, v[74:77], s[24:25] offset:0
	global_store_dwordx4 v2, v[78:81], s[24:25] offset:1024
	global_store_dwordx4 v2, v[82:85], s[24:25] offset:2048
	global_store_dwordx4 v2, v[86:89], s[24:25] offset:3072
	global_store_dwordx4 v3, v[90:93], s[24:25] offset:0
	global_store_dwordx4 v3, v[94:97], s[24:25] offset:1024
	global_store_dwordx4 v3, v[98:101], s[24:25] offset:2048
	global_store_dwordx4 v3, v[102:105], s[24:25] offset:3072
	s_waitcnt vmcnt(8)
	v_mov_b32_e32 v9, 0
	v_lshlrev_b32_e32 v5, 16, v154
	v_and_b32_e32 v6, 0xffff0000, v154
	v_lshlrev_b32_e32 v7, 16, v155
	v_and_b32_e32 v8, 0xffff0000, v155
	v_mul_f32_e32 v174, v5, v5
	v_fmac_f32_e32 v174, v6, v6
	v_mul_f32_e32 v175, v7, v7
	v_fmac_f32_e32 v175, v8, v8
	v_add_f32_e32 v174, v174, v175
	v_add_f32_e32 v9, v9, v174
	v_lshlrev_b32_e32 v5, 16, v156
	v_and_b32_e32 v6, 0xffff0000, v156
	v_lshlrev_b32_e32 v7, 16, v157
	v_and_b32_e32 v8, 0xffff0000, v157
	v_mul_f32_e32 v174, v5, v5
	v_fmac_f32_e32 v174, v6, v6
	v_mul_f32_e32 v175, v7, v7
	v_fmac_f32_e32 v175, v8, v8
	v_add_f32_e32 v174, v174, v175
	v_add_f32_e32 v9, v9, v174
	v_lshlrev_b32_e32 v5, 16, v158
	v_and_b32_e32 v6, 0xffff0000, v158
	v_lshlrev_b32_e32 v7, 16, v159
	v_and_b32_e32 v8, 0xffff0000, v159
	v_mul_f32_e32 v174, v5, v5
	v_fmac_f32_e32 v174, v6, v6
	v_mul_f32_e32 v175, v7, v7
	v_fmac_f32_e32 v175, v8, v8
	v_add_f32_e32 v174, v174, v175
	v_add_f32_e32 v9, v9, v174
	v_lshlrev_b32_e32 v5, 16, v160
	v_and_b32_e32 v6, 0xffff0000, v160
	v_lshlrev_b32_e32 v7, 16, v161
	v_and_b32_e32 v8, 0xffff0000, v161
	v_mul_f32_e32 v174, v5, v5
	v_fmac_f32_e32 v174, v6, v6
	v_mul_f32_e32 v175, v7, v7
	v_fmac_f32_e32 v175, v8, v8
	v_add_f32_e32 v174, v174, v175
	v_add_f32_e32 v9, v9, v174
	v_lshlrev_b32_e32 v5, 16, v162
	v_and_b32_e32 v6, 0xffff0000, v162
	v_lshlrev_b32_e32 v7, 16, v163
	v_and_b32_e32 v8, 0xffff0000, v163
	v_mul_f32_e32 v174, v5, v5
	v_fmac_f32_e32 v174, v6, v6
	v_mul_f32_e32 v175, v7, v7
	v_fmac_f32_e32 v175, v8, v8
	v_add_f32_e32 v174, v174, v175
	v_add_f32_e32 v9, v9, v174
	v_lshlrev_b32_e32 v5, 16, v166
	v_and_b32_e32 v6, 0xffff0000, v166
	v_lshlrev_b32_e32 v7, 16, v167
	v_and_b32_e32 v8, 0xffff0000, v167
	v_mul_f32_e32 v174, v5, v5
	v_fmac_f32_e32 v174, v6, v6
	v_mul_f32_e32 v175, v7, v7
	v_fmac_f32_e32 v175, v8, v8
	v_add_f32_e32 v174, v174, v175
	v_add_f32_e32 v9, v9, v174
	v_lshlrev_b32_e32 v5, 16, v168
	v_and_b32_e32 v6, 0xffff0000, v168
	v_lshlrev_b32_e32 v7, 16, v169
	v_and_b32_e32 v8, 0xffff0000, v169
	v_mul_f32_e32 v174, v5, v5
	v_fmac_f32_e32 v174, v6, v6
	v_mul_f32_e32 v175, v7, v7
	v_fmac_f32_e32 v175, v8, v8
	v_add_f32_e32 v174, v174, v175
	v_add_f32_e32 v9, v9, v174
	v_lshlrev_b32_e32 v5, 16, v172
	v_and_b32_e32 v6, 0xffff0000, v172
	v_lshlrev_b32_e32 v7, 16, v173
	v_and_b32_e32 v8, 0xffff0000, v173
	v_mul_f32_e32 v174, v5, v5
	v_fmac_f32_e32 v174, v6, v6
	v_mul_f32_e32 v175, v7, v7
	v_fmac_f32_e32 v175, v8, v8
	v_add_f32_e32 v174, v174, v175
	v_add_f32_e32 v9, v9, v174
; __global__ void __launch_bounds__(512, 2) mega_fwd(Args a) {
;     ...
;       const float r = rsqrtf(wave_sum(ss) * (1.f / DM) + EPS);
; #pragma unroll
;       for (int j = 0; j < 8; ++j) { const f32x4 gn = *(const f32x4*)(g2 + 4 * (64 * j + lane)); float* yp = out + O_Y + (size_t)m * DM + 4 * (64 * j + lane);
;         *(f32x4*)yp = hin[j] + v[j] * r * gn; }
	s_nop 1
	v_add_f32_dpp v9, v9, v9 quad_perm:[1,0,3,2] row_mask:0xf bank_mask:0xf
	s_nop 1
	v_add_f32_dpp v9, v9, v9 quad_perm:[2,3,0,1] row_mask:0xf bank_mask:0xf
	s_nop 1
	v_add_f32_dpp v9, v9, v9 row_half_mirror row_mask:0xf bank_mask:0xf
	s_nop 1
	v_add_f32_dpp v9, v9, v9 row_mirror row_mask:0xf bank_mask:0xf
	s_nop 1
	v_add_f32_dpp v9, v9, v9 row_bcast:15 row_mask:0xa bank_mask:0xf
	s_nop 1
	v_add_f32_dpp v9, v9, v9 row_bcast:31 row_mask:0xc bank_mask:0xf
	s_nop 1
	v_readlane_b32 s79, v9, 63
	s_nop 1
	v_mov_b32_e32 v174, s79
	v_fmamk_f32 v174, v174, 0x3a000000, v177
	v_rsq_f32_e32 v176, v174
	s_nop 0
	v_lshlrev_b32_e32 v5, 16, v154
	v_and_b32_e32 v6, 0xffff0000, v154
	v_lshlrev_b32_e32 v7, 16, v155
	v_and_b32_e32 v8, 0xffff0000, v155
	v_mul_f32_e32 v5, v5, v176
	v_mul_f32_e32 v6, v6, v176
	v_mul_f32_e32 v7, v7, v176
	v_mul_f32_e32 v8, v8, v176
	v_fmac_f32_e32 v106, v5, v10
	v_fmac_f32_e32 v107, v6, v11
	v_fmac_f32_e32 v108, v7, v12
	v_fmac_f32_e32 v109, v8, v13
	v_lshlrev_b32_e32 v5, 16, v156
	v_and_b32_e32 v6, 0xffff0000, v156
	v_lshlrev_b32_e32 v7, 16, v157
	v_and_b32_e32 v8, 0xffff0000, v157
	v_mul_f32_e32 v5, v5, v176
	v_mul_f32_e32 v6, v6, v176
	v_mul_f32_e32 v7, v7, v176
	v_mul_f32_e32 v8, v8, v176
	v_fmac_f32_e32 v110, v5, v14
	v_fmac_f32_e32 v111, v6, v15
	v_fmac_f32_e32 v112, v7, v16
	v_fmac_f32_e32 v113, v8, v17
	v_lshlrev_b32_e32 v5, 16, v158
	v_and_b32_e32 v6, 0xffff0000, v158
	v_lshlrev_b32_e32 v7, 16, v159
	v_and_b32_e32 v8, 0xffff0000, v159
	v_mul_f32_e32 v5, v5, v176
	v_mul_f32_e32 v6, v6, v176
	v_mul_f32_e32 v7, v7, v176
	v_mul_f32_e32 v8, v8, v176
	v_fmac_f32_e32 v114, v5, v18
	v_fmac_f32_e32 v115, v6, v19
	v_fmac_f32_e32 v116, v7, v20
	v_fmac_f32_e32 v117, v8, v21
	v_lshlrev_b32_e32 v5, 16, v160
	v_and_b32_e32 v6, 0xffff0000, v160
	v_lshlrev_b32_e32 v7, 16, v161
	v_and_b32_e32 v8, 0xffff0000, v161
	v_mul_f32_e32 v5, v5, v176
	v_mul_f32_e32 v6, v6, v176
	v_mul_f32_e32 v7, v7, v176
	v_mul_f32_e32 v8, v8, v176
	v_fmac_f32_e32 v118, v5, v22
	v_fmac_f32_e32 v119, v6, v23
	v_fmac_f32_e32 v120, v7, v24
	v_fmac_f32_e32 v121, v8, v25
	v_lshlrev_b32_e32 v5, 16, v162
	v_and_b32_e32 v6, 0xffff0000, v162
	v_lshlrev_b32_e32 v7, 16, v163
	v_and_b32_e32 v8, 0xffff0000, v163
	v_mul_f32_e32 v5, v5, v176
	v_mul_f32_e32 v6, v6, v176
	v_mul_f32_e32 v7, v7, v176
	v_mul_f32_e32 v8, v8, v176
	v_fmac_f32_e32 v122, v5, v26
	v_fmac_f32_e32 v123, v6, v27
	v_fmac_f32_e32 v124, v7, v28
	v_fmac_f32_e32 v125, v8, v29
	v_lshlrev_b32_e32 v5, 16, v166
	v_and_b32_e32 v6, 0xffff0000, v166
	v_lshlrev_b32_e32 v7, 16, v167
	v_and_b32_e32 v8, 0xffff0000, v167
	v_mul_f32_e32 v5, v5, v176
	v_mul_f32_e32 v6, v6, v176
	v_mul_f32_e32 v7, v7, v176
	v_mul_f32_e32 v8, v8, v176
	v_fmac_f32_e32 v126, v5, v30
	v_fmac_f32_e32 v127, v6, v31
	v_fmac_f32_e32 v128, v7, v32
	v_fmac_f32_e32 v129, v8, v33
	v_lshlrev_b32_e32 v5, 16, v168
	v_and_b32_e32 v6, 0xffff0000, v168
	v_lshlrev_b32_e32 v7, 16, v169
	v_and_b32_e32 v8, 0xffff0000, v169
	v_mul_f32_e32 v5, v5, v176
	v_mul_f32_e32 v6, v6, v176
	v_mul_f32_e32 v7, v7, v176
	v_mul_f32_e32 v8, v8, v176
	v_fmac_f32_e32 v130, v5, v34
	v_fmac_f32_e32 v131, v6, v35
	v_fmac_f32_e32 v132, v7, v36
	v_fmac_f32_e32 v133, v8, v37
	v_lshlrev_b32_e32 v5, 16, v172
	v_and_b32_e32 v6, 0xffff0000, v172
	v_lshlrev_b32_e32 v7, 16, v173
	v_and_b32_e32 v8, 0xffff0000, v173
	v_mul_f32_e32 v5, v5, v176
	v_mul_f32_e32 v6, v6, v176
	v_mul_f32_e32 v7, v7, v176
	v_mul_f32_e32 v8, v8, v176
	v_fmac_f32_e32 v134, v5, v38
	v_fmac_f32_e32 v135, v6, v39
	v_fmac_f32_e32 v136, v7, v40
	v_fmac_f32_e32 v137, v8, v41
	global_store_dwordx4 v2, v[106:109], s[28:29] offset:0
	global_store_dwordx4 v2, v[110:113], s[28:29] offset:1024
	global_store_dwordx4 v2, v[114:117], s[28:29] offset:2048
	global_store_dwordx4 v2, v[118:121], s[28:29] offset:3072
	global_store_dwordx4 v3, v[122:125], s[28:29] offset:0
	global_store_dwordx4 v3, v[126:129], s[28:29] offset:1024
	global_store_dwordx4 v3, v[130:133], s[28:29] offset:2048
	global_store_dwordx4 v3, v[134:137], s[28:29] offset:3072
	s_add_u32 s18, s19, s78
	s_branch .Lew9_loop
; __device__ __forceinline__ float bflo(unsigned w) { return __uint_as_float(w << 16); }
; __device__ __forceinline__ float bfhi(unsigned w) { return __uint_as_float(w & 0xffff0000u); }
; __global__ void __launch_bounds__(512, 2) mega_fwd(Args a) {
;     ...
;       for (int j = 0; j < 8; ++j) hin[j] = *(const f32x4*)(out + O_Y + (size_t)m * DM + 4 * (64 * j + lane));
;       f32x4 v[8]; float ss = 0.f;
; #pragma unroll
;       for (int j = 0; j < 8; ++j) {
;         if (m < MP) { const u32x2 w = *(const u32x2*)(MO + (size_t)m * DM + 4 * (64 * j + lane)); v[j] = (f32x4){bflo(w.x), bfhi(w.x), bflo(w.y), bfhi(w.y)}; }
;         else { v[j] = (f32x4){0.f, 0.f, 0.f, 0.f};
; #pragma unroll
;           for (int ks = 0; ks < 16; ++ks) v[j] += *(const f32x4*)(PART + ((size_t)ks * MSAMP + (m - MP)) * DM + 4 * (64 * j + lane)); }
;         ss += (v[j].x * v[j].x + v[j].y * v[j].y) + (v[j].z * v[j].z + v[j].w * v[j].w); }
;       const float r = rsqrtf(wave_sum(ss) * (1.f / DM) + EPS);
; #pragma unroll
;       for (int j = 0; j < 8; ++j) { const f32x4 gn = *(const f32x4*)(g2 + 4 * (64 * j + lane)); float* yp = out + O_Y + (size_t)m * DM + 4 * (64 * j + lane);
;         *(f32x4*)yp = hin[j] + v[j] * r * gn; }
.Lew9_single:
	s_waitcnt vmcnt(0)
	v_mov_b32_e32 v9, 0
	v_lshlrev_b32_e32 v5, 16, v138
	v_and_b32_e32 v6, 0xffff0000, v138
	v_lshlrev_b32_e32 v7, 16, v139
	v_and_b32_e32 v8, 0xffff0000, v139
	v_mul_f32_e32 v174, v5, v5
	v_fmac_f32_e32 v174, v6, v6
	v_mul_f32_e32 v175, v7, v7
	v_fmac_f32_e32 v175, v8, v8
	v_add_f32_e32 v174, v174, v175
	v_add_f32_e32 v9, v9, v174
	v_lshlrev_b32_e32 v5, 16, v140
	v_and_b32_e32 v6, 0xffff0000, v140
	v_lshlrev_b32_e32 v7, 16, v141
	v_and_b32_e32 v8, 0xffff0000, v141
	v_mul_f32_e32 v174, v5, v5
	v_fmac_f32_e32 v174, v6, v6
	v_mul_f32_e32 v175, v7, v7
	v_fmac_f32_e32 v175, v8, v8
	v_add_f32_e32 v174, v174, v175
	v_add_f32_e32 v9, v9, v174
	v_lshlrev_b32_e32 v5, 16, v142
	v_and_b32_e32 v6, 0xffff0000, v142
	v_lshlrev_b32_e32 v7, 16, v143
	v_and_b32_e32 v8, 0xffff0000, v143
	v_mul_f32_e32 v174, v5, v5
	v_fmac_f32_e32 v174, v6, v6
	v_mul_f32_e32 v175, v7, v7
	v_fmac_f32_e32 v175, v8, v8
	v_add_f32_e32 v174, v174, v175
	v_add_f32_e32 v9, v9, v174
	v_lshlrev_b32_e32 v5, 16, v144
	v_and_b32_e32 v6, 0xffff0000, v144
	v_lshlrev_b32_e32 v7, 16, v145
	v_and_b32_e32 v8, 0xffff0000, v145
	v_mul_f32_e32 v174, v5, v5
	v_fmac_f32_e32 v174, v6, v6
	v_mul_f32_e32 v175, v7, v7
	v_fmac_f32_e32 v175, v8, v8
	v_add_f32_e32 v174, v174, v175
	v_add_f32_e32 v9, v9, v174
	v_lshlrev_b32_e32 v5, 16, v146
	v_and_b32_e32 v6, 0xffff0000, v146
	v_lshlrev_b32_e32 v7, 16, v147
	v_and_b32_e32 v8, 0xffff0000, v147
	v_mul_f32_e32 v174, v5, v5
	v_fmac_f32_e32 v174, v6, v6
	v_mul_f32_e32 v175, v7, v7
	v_fmac_f32_e32 v175, v8, v8
	v_add_f32_e32 v174, v174, v175
	v_add_f32_e32 v9, v9, v174
	v_lshlrev_b32_e32 v5, 16, v148
	v_and_b32_e32 v6, 0xffff0000, v148
	v_lshlrev_b32_e32 v7, 16, v149
	v_and_b32_e32 v8, 0xffff0000, v149
	v_mul_f32_e32 v174, v5, v5
	v_fmac_f32_e32 v174, v6, v6
	v_mul_f32_e32 v175, v7, v7
	v_fmac_f32_e32 v175, v8, v8
	v_add_f32_e32 v174, v174, v175
	v_add_f32_e32 v9, v9, v174
	v_lshlrev_b32_e32 v5, 16, v150
	v_and_b32_e32 v6, 0xffff0000, v150
	v_lshlrev_b32_e32 v7, 16, v151
	v_and_b32_e32 v8, 0xffff0000, v151
	v_mul_f32_e32 v174, v5, v5
	v_fmac_f32_e32 v174, v6, v6
	v_mul_f32_e32 v175, v7, v7
	v_fmac_f32_e32 v175, v8, v8
	v_add_f32_e32 v174, v174, v175
	v_add_f32_e32 v9, v9, v174
	v_lshlrev_b32_e32 v5, 16, v152
	v_and_b32_e32 v6, 0xffff0000, v152
	v_lshlrev_b32_e32 v7, 16, v153
	v_and_b32_e32 v8, 0xffff0000, v153
	v_mul_f32_e32 v174, v5, v5
	v_fmac_f32_e32 v174, v6, v6
	v_mul_f32_e32 v175, v7, v7
	v_fmac_f32_e32 v175, v8, v8
	v_add_f32_e32 v174, v174, v175
	v_add_f32_e32 v9, v9, v174
	s_nop 1
	v_add_f32_dpp v9, v9, v9 quad_perm:[1,0,3,2] row_mask:0xf bank_mask:0xf
	s_nop 1
	v_add_f32_dpp v9, v9, v9 quad_perm:[2,3,0,1] row_mask:0xf bank_mask:0xf
	s_nop 1
	v_add_f32_dpp v9, v9, v9 row_half_mirror row_mask:0xf bank_mask:0xf
	s_nop 1
	v_add_f32_dpp v9, v9, v9 row_mirror row_mask:0xf bank_mask:0xf
	s_nop 1
	v_add_f32_dpp v9, v9, v9 row_bcast:15 row_mask:0xa bank_mask:0xf
	s_nop 1
	v_add_f32_dpp v9, v9, v9 row_bcast:31 row_mask:0xc bank_mask:0xf
	s_nop 1
	v_readlane_b32 s79, v9, 63
	s_nop 1
	v_mov_b32_e32 v174, s79
	v_fmamk_f32 v174, v174, 0x3a000000, v177
	v_rsq_f32_e32 v176, v174
	s_nop 0
	v_lshlrev_b32_e32 v5, 16, v138
	v_and_b32_e32 v6, 0xffff0000, v138
	v_lshlrev_b32_e32 v7, 16, v139
	v_and_b32_e32 v8, 0xffff0000, v139
	v_mul_f32_e32 v5, v5, v176
	v_mul_f32_e32 v6, v6, v176
	v_mul_f32_e32 v7, v7, v176
	v_mul_f32_e32 v8, v8, v176
	v_fmac_f32_e32 v74, v5, v10
	v_fmac_f32_e32 v75, v6, v11
	v_fmac_f32_e32 v76, v7, v12
	v_fmac_f32_e32 v77, v8, v13
	v_lshlrev_b32_e32 v5, 16, v140
	v_and_b32_e32 v6, 0xffff0000, v140
	v_lshlrev_b32_e32 v7, 16, v141
	v_and_b32_e32 v8, 0xffff0000, v141
	v_mul_f32_e32 v5, v5, v176
	v_mul_f32_e32 v6, v6, v176
	v_mul_f32_e32 v7, v7, v176
	v_mul_f32_e32 v8, v8, v176
	v_fmac_f32_e32 v78, v5, v14
	v_fmac_f32_e32 v79, v6, v15
	v_fmac_f32_e32 v80, v7, v16
	v_fmac_f32_e32 v81, v8, v17
	v_lshlrev_b32_e32 v5, 16, v142
	v_and_b32_e32 v6, 0xffff0000, v142
	v_lshlrev_b32_e32 v7, 16, v143
	v_and_b32_e32 v8, 0xffff0000, v143
	v_mul_f32_e32 v5, v5, v176
	v_mul_f32_e32 v6, v6, v176
	v_mul_f32_e32 v7, v7, v176
	v_mul_f32_e32 v8, v8, v176
	v_fmac_f32_e32 v82, v5, v18
	v_fmac_f32_e32 v83, v6, v19
	v_fmac_f32_e32 v84, v7, v20
	v_fmac_f32_e32 v85, v8, v21
	v_lshlrev_b32_e32 v5, 16, v144
	v_and_b32_e32 v6, 0xffff0000, v144
	v_lshlrev_b32_e32 v7, 16, v145
	v_and_b32_e32 v8, 0xffff0000, v145
	v_mul_f32_e32 v5, v5, v176
	v_mul_f32_e32 v6, v6, v176
	v_mul_f32_e32 v7, v7, v176
	v_mul_f32_e32 v8, v8, v176
	v_fmac_f32_e32 v86, v5, v22
	v_fmac_f32_e32 v87, v6, v23
	v_fmac_f32_e32 v88, v7, v24
	v_fmac_f32_e32 v89, v8, v25
	v_lshlrev_b32_e32 v5, 16, v146
	v_and_b32_e32 v6, 0xffff0000, v146
	v_lshlrev_b32_e32 v7, 16, v147
	v_and_b32_e32 v8, 0xffff0000, v147
	v_mul_f32_e32 v5, v5, v176
	v_mul_f32_e32 v6, v6, v176
	v_mul_f32_e32 v7, v7, v176
	v_mul_f32_e32 v8, v8, v176
	v_fmac_f32_e32 v90, v5, v26
	v_fmac_f32_e32 v91, v6, v27
	v_fmac_f32_e32 v92, v7, v28
	v_fmac_f32_e32 v93, v8, v29
	v_lshlrev_b32_e32 v5, 16, v148
	v_and_b32_e32 v6, 0xffff0000, v148
	v_lshlrev_b32_e32 v7, 16, v149
	v_and_b32_e32 v8, 0xffff0000, v149
	v_mul_f32_e32 v5, v5, v176
	v_mul_f32_e32 v6, v6, v176
	v_mul_f32_e32 v7, v7, v176
	v_mul_f32_e32 v8, v8, v176
	v_fmac_f32_e32 v94, v5, v30
	v_fmac_f32_e32 v95, v6, v31
	v_fmac_f32_e32 v96, v7, v32
	v_fmac_f32_e32 v97, v8, v33
	v_lshlrev_b32_e32 v5, 16, v150
	v_and_b32_e32 v6, 0xffff0000, v150
	v_lshlrev_b32_e32 v7, 16, v151
	v_and_b32_e32 v8, 0xffff0000, v151
	v_mul_f32_e32 v5, v5, v176
	v_mul_f32_e32 v6, v6, v176
	v_mul_f32_e32 v7, v7, v176
	v_mul_f32_e32 v8, v8, v176
	v_fmac_f32_e32 v98, v5, v34
	v_fmac_f32_e32 v99, v6, v35
	v_fmac_f32_e32 v100, v7, v36
	v_fmac_f32_e32 v101, v8, v37
	v_lshlrev_b32_e32 v5, 16, v152
	v_and_b32_e32 v6, 0xffff0000, v152
	v_lshlrev_b32_e32 v7, 16, v153
	v_and_b32_e32 v8, 0xffff0000, v153
	v_mul_f32_e32 v5, v5, v176
	v_mul_f32_e32 v6, v6, v176
	v_mul_f32_e32 v7, v7, v176
	v_mul_f32_e32 v8, v8, v176
	v_fmac_f32_e32 v102, v5, v38
	v_fmac_f32_e32 v103, v6, v39
	v_fmac_f32_e32 v104, v7, v40
	v_fmac_f32_e32 v105, v8, v41
	global_store_dwordx4 v2, v[74:77], s[24:25] offset:0
	global_store_dwordx4 v2, v[78:81], s[24:25] offset:1024
	global_store_dwordx4 v2, v[82:85], s[24:25] offset:2048
	global_store_dwordx4 v2, v[86:89], s[24:25] offset:3072
	global_store_dwordx4 v3, v[90:93], s[24:25] offset:0
	global_store_dwordx4 v3, v[94:97], s[24:25] offset:1024
	global_store_dwordx4 v3, v[98:101], s[24:25] offset:2048
	global_store_dwordx4 v3, v[102:105], s[24:25] offset:3072
.Lew9_done:
.LBB0_1591:
	s_endpgm
